# attention bodies: 68 v_pk_fma_f32 (op_sel_hi:[1,0,0], scalar multiplier) beside MFMAs split into two v_fma_f32 each; bit-identical
# speedup vs baseline: 1.0007x; 1.0007x over previous
; __device__ __forceinline__ int fresh_lane() { int l; asm volatile("v_mbcnt_lo_u32_b32 %0, -1, 0\n\tv_mbcnt_hi_u32_b32 %0, -1, %0" : "=v"(l)); return l; }
; template <int MODE>
; __device__ __forceinline__ void body(const Desc& d, char* lds, int wave_id) {
;     ...
;   int tid_l = wave_id * 64 + fresh_lane(); asm volatile("" : "+v"(tid_l));
;   const int tid = tid_l, wid = tid >> 6, lane = tid & 63, r32 = lane & 31, hi = lane >> 5;
;   char* V_lds = lds + OFF_V; char* K_lds = lds + OFF_K; char* KR_lds = lds + OFF_KR;
;   float* ws = (float*)(lds + OFF_WS) + wid * 128; float* li_l = ws; float* al_l = ws + 32; float* w2_l = ws + 64;
;   float m_reg = -1e30f, l_reg = 0; f32x16 o[4] = {}; bf16x8 qr[NQ];
;   const int vq = wid * 32 + r32;
;   const int qtok = (MODE == 0) ? tokA<MODE>(d, vq) : d.qrow0 + vq;
;   { const bf16_t* Qw = d.Q + (size_t)qtok * d.ldq + hi * 8;
; #pragma unroll
;     for (int d0 = 0; d0 < NQ; ++d0) qr[d0] = *reinterpret_cast<const bf16x8*>(Qw + d0 * 16);
;     if constexpr (MODE == 1) {
;       const f32x2* rp = d.rope + (size_t)(d.pos0 + vq) * 32 + hi * 8;
; #pragma unroll
;       for (int dd = 0; dd < 2; ++dd) { bf16x8 x1 = qr[8 + dd], x2 = qr[10 + dd]; bf16x8 y1, y2;
; #pragma unroll
;         for (int e = 0; e < 8; ++e) { const f32x2 cs = rp[dd * 16 + e]; const float a = bf2f((unsigned short)x1[e]), b = bf2f((unsigned short)x2[e]);
;           const float o1 = a * cs.x - b * cs.y, o2 = b * cs.x + a * cs.y; const unsigned pk = cvt_pk_bf16(o1, o2); y1[e] = (short)(pk & 0xffff); y2[e] = (short)(pk >> 16); }
;         qr[8 + dd] = y1; qr[10 + dd] = y2; }
; __global__ void __launch_bounds__(512) mega_fwd(Params P) {
;     ...
;                     if (i < N_MLA_L) { const int b = i & 255, rnd = i >> 8, pair = rnd * 8 + (b & 7); s = pair / 6; h = pair % 6; qb = b >> 3; }
;                     else { const int k = i - N_MLA_L; const int pair = k >> 3; s = 4 + pair / 6; h = pair % 6; qb = k & 7; }
;                     int st, len; seq_of(s, st, len);
;                     att::Desc d{}; d.Q = QB + h * 192; d.ldq = 1280; d.K = KV + h * 256; d.V = KV + h * 256 + 128; d.ldk = 1536; d.KR = KR2; d.O = YB + h * 128; d.ldo = 768;
;                     d.qrow0 = st + qb * 256; d.kvrow0 = st; d.NT = len / 64; const float sc = 0.07216878364870323f; d.C = sc * 1.4426950408889634f; d.THRS = att::THR / sc; d.rope = ROPE; d.pos0 = qb * 256;
.LBB0_796:
	s_lshl_b32 s38, s46, 11
	s_add_i32 s44, s38, 0x6000
	s_mul_i32 s38, s69, 0xc0
	s_ashr_i32 s39, s38, 31
	s_lshl_b32 s45, s46, 13
	s_lshl_b64 s[38:39], s[38:39], 1
	s_add_u32 s38, s55, s38
	s_addc_u32 s39, s64, s39
	s_lshl_b32 s40, s69, 8
	s_ashr_i32 s41, s40, 31
	s_lshl_b64 s[40:41], s[40:41], 1
	s_add_u32 s60, s65, s40
	s_addc_u32 s61, s66, s41
	s_lshl_b32 s40, s47, 8
	s_cmp_lt_i32 s46, 4
	s_waitcnt vmcnt(0)
	s_barrier
	v_mbcnt_lo_u32_b32 v0, -1, 0
	v_mbcnt_hi_u32_b32 v0, -1, v0
	s_cselect_b32 s44, s45, s44
	v_add_u32_e32 v48, s29, v0
	s_cselect_b32 s70, 0x80, 32
	v_ashrrev_i32_e32 v0, 6, v48
	v_and_b32_e32 v168, 31, v48
	s_add_i32 s41, s44, s40
	v_lshl_or_b32 v8, v0, 5, v168
	v_add_u32_e32 v171, s41, v8
	v_add_u32_e32 v8, s40, v8
	s_add_i32 s45, 0, 0x14000
	v_ashrrev_i32_e32 v9, 31, v8
	v_bfe_u32 v169, v48, 5, 1
	v_lshl_add_u32 v170, v0, 9, s45
	v_mov_b64_e32 v[0:1], s[38:39]
	s_movk_i32 s38, 0xa00
	v_lshlrev_b64 v[8:9], 8, v[8:9]
	v_mad_i64_i32 v[0:1], s[38:39], v171, s38, v[0:1]
	v_lshlrev_b32_e32 v194, 4, v169
	v_lshl_add_u64 v[8:9], s[50:51], 0, v[8:9]
	v_lshlrev_b32_e32 v18, 6, v169
	v_mov_b32_e32 v19, v195
	v_lshl_add_u64 v[4:5], v[0:1], 0, v[194:195]
	v_lshl_add_u64 v[8:9], v[8:9], 0, v[18:19]
	global_load_dwordx4 v[124:127], v[4:5], off
	global_load_dwordx4 v[120:123], v[4:5], off offset:32
	global_load_dwordx4 v[116:119], v[4:5], off offset:64
	global_load_dwordx4 v[112:115], v[4:5], off offset:96
	global_load_dwordx4 v[108:111], v[4:5], off offset:128
	global_load_dwordx4 v[104:107], v[4:5], off offset:160
	global_load_dwordx4 v[100:103], v[4:5], off offset:192
	global_load_dwordx4 v[96:99], v[4:5], off offset:224
	global_load_dwordx4 v[10:13], v[4:5], off offset:256
	global_load_dwordx4 v[0:3], v[4:5], off offset:288
	global_load_dwordx4 v[14:17], v[4:5], off offset:320
	s_nop 0
	global_load_dwordx4 v[4:7], v[4:5], off offset:352
	v_ashrrev_i32_e32 v53, 4, v48
	global_load_dwordx2 v[18:19], v[8:9], off
	global_load_dwordx4 v[128:131], v[8:9], off
	global_load_dwordx4 v[132:135], v[8:9], off offset:16
	global_load_dwordx4 v[136:139], v[8:9], off offset:32
	global_load_dwordx4 v[140:143], v[8:9], off offset:48
	global_load_dwordx4 v[222:225], v[8:9], off offset:128
	global_load_dwordx4 v[226:229], v[8:9], off offset:144
	global_load_dwordx4 v[230:233], v[8:9], off offset:160
	global_load_dwordx4 v[234:237], v[8:9], off offset:176
	v_add_u32_e32 v54, 32, v53
	v_and_b32_e32 v49, 63, v48
	v_add_u32_e32 v50, s44, v53
	v_ashrrev_i32_e32 v55, 3, v48
	s_cmp_lg_u32 0, -1
	s_movk_i32 s38, 0x70
	s_cselect_b32 s46, 0, 0
	s_add_i32 s45, 0, 0x10000
	v_lshlrev_b32_e32 v75, 8, v168
	v_or_b32_e32 v84, 32, v194
	v_or_b32_e32 v85, 64, v194
	v_or_b32_e32 v86, 0x60, v194
	s_mov_b32 s81, s80
	s_mov_b32 s82, s80
	s_mov_b32 s83, s80
	s_mov_b32 s84, s80
	s_mov_b32 s85, s80
	s_mov_b32 s86, s80
	s_mov_b32 s87, s80
	s_mov_b32 s88, s80
	s_mov_b32 s89, s80
	s_mov_b32 s90, s80
	s_mov_b32 s91, s80
	s_mov_b32 s92, s80
	s_mov_b32 s93, s80
	s_mov_b32 s94, s80
	s_mov_b32 s95, s80
	s_mov_b32 s71, 2
	v_lshl_add_u32 v173, v168, 2, v170
	v_mov_b32_e32 v179, 0
	s_waitcnt vmcnt(4)
	v_lshlrev_b32_e32 v20, 16, v10
	s_waitcnt vmcnt(2)
	v_lshlrev_b32_e32 v21, 16, v14
	s_waitcnt vmcnt(0)
	v_pk_mul_f32 v[22:23], v[18:19], v[20:21]
	v_pk_mul_f32 v[18:19], v[18:19], v[20:21] op_sel:[1,0] op_sel_hi:[0,1]
	v_add_f32_e32 v18, v18, v19
	v_sub_f32_e32 v22, v22, v23
	v_cvt_pk_bf16_f32 v57, v22, v18
	v_mov_b32_e32 v18, v130
	v_mov_b32_e32 v19, v131
	v_and_b32_e32 v21, 0xffff0000, v14
	v_and_b32_e32 v20, 0xffff0000, v10
	s_waitcnt vmcnt(0)
	v_pk_mul_f32 v[22:23], v[18:19], v[20:21]
	v_pk_mul_f32 v[18:19], v[18:19], v[20:21] op_sel:[0,1] op_sel_hi:[1,0]
	v_sub_f32_e32 v10, v22, v23
	v_add_f32_e32 v14, v18, v19
	v_cvt_pk_bf16_f32 v58, v10, v14
	v_mov_b32_e32 v18, v132
	v_mov_b32_e32 v19, v133
	v_lshlrev_b32_e32 v21, 16, v15
	v_lshlrev_b32_e32 v20, 16, v11
	v_and_b32_e32 v15, 0xffff0000, v15
	s_waitcnt vmcnt(0)
	v_pk_mul_f32 v[22:23], v[18:19], v[20:21]
	v_pk_mul_f32 v[18:19], v[18:19], v[20:21] op_sel:[0,1] op_sel_hi:[1,0]
	v_sub_f32_e32 v10, v22, v23
	v_add_f32_e32 v14, v18, v19
	v_cvt_pk_bf16_f32 v59, v10, v14
	v_mov_b32_e32 v18, v134
	v_mov_b32_e32 v19, v135
	v_and_b32_e32 v14, 0xffff0000, v11
	s_waitcnt vmcnt(0)
	v_pk_mul_f32 v[10:11], v[18:19], v[14:15]
	s_nop 0
	v_sub_f32_e32 v20, v10, v11
	v_pk_mul_f32 v[10:11], v[18:19], v[14:15] op_sel:[0,1] op_sel_hi:[1,0]
	v_lshlrev_b32_e32 v15, 16, v16
	v_add_f32_e32 v10, v10, v11
	v_cvt_pk_bf16_f32 v60, v20, v10
	v_mov_b32_e32 v10, v136
	v_mov_b32_e32 v11, v137
	v_lshlrev_b32_e32 v14, 16, v12
	s_waitcnt vmcnt(0)
	v_pk_mul_f32 v[18:19], v[10:11], v[14:15]
	v_pk_mul_f32 v[10:11], v[10:11], v[14:15] op_sel:[0,1] op_sel_hi:[1,0]
	v_sub_f32_e32 v18, v18, v19
	v_add_f32_e32 v10, v10, v11
	v_cvt_pk_bf16_f32 v61, v18, v10
	v_mov_b32_e32 v10, v138
	v_mov_b32_e32 v11, v139
	v_and_b32_e32 v15, 0xffff0000, v16
	v_and_b32_e32 v14, 0xffff0000, v12
	v_lshlrev_b32_e32 v16, 4, v48
	v_and_b32_e32 v62, 0x70, v16
	v_bitop3_b32 v76, v84, v75, v62 bitop3:0xde
	v_add_u32_e32 v181, 0, v76
	s_waitcnt vmcnt(0)
	v_pk_mul_f32 v[18:19], v[10:11], v[14:15]
	v_pk_mul_f32 v[10:11], v[10:11], v[14:15] op_sel:[0,1] op_sel_hi:[1,0]
	v_sub_f32_e32 v12, v18, v19
	v_add_f32_e32 v10, v10, v11
	v_cvt_pk_bf16_f32 v63, v12, v10
	v_mov_b32_e32 v10, v140
	v_mov_b32_e32 v11, v141
	v_lshlrev_b32_e32 v15, 16, v17
	v_lshlrev_b32_e32 v14, 16, v13
	s_waitcnt vmcnt(0)
; __device__ __forceinline__ unsigned cvt_pk_bf16(float lo, float hi) { unsigned r; asm volatile("v_cvt_pk_bf16_f32 %0, %1, %2" : "=v"(r) : "v"(lo), "v"(hi)); return r; }
; __device__ __forceinline__ float bf2f(unsigned short h) { return __uint_as_float(((unsigned)h) << 16); }
; __device__ __forceinline__ int v_st(int k, int c) { const int kk = (k & ~0xC) | ((k & 4) << 1) | ((k & 8) >> 1); return ((kk >> 3) * 4 + (c >> 5)) * 512 + ((kk & 7) * 32 + (c & 31)) * 2; }
; __device__ __forceinline__ int v_rd_base(int lane) { return ((lane & 3) << 3) | (((lane >> 2) & 3) << 6) | (((lane >> 4) & 1) << 5) | (((lane >> 5) & 1) << 8); }
; #define SWRITE(b, i) do { *(bf16x8*)(V_lds + (b) * SHM_V + vst0) = sr_[i].vs0; *(bf16x8*)(V_lds + (b) * SHM_V + vst1) = sr_[i].vs1; const int kc = sc * 2; \
;     *(bf16x8*)(K_lds + (b) * SHM_K + KSWZ(sr, kc)) = sr_[i].ks0; *(bf16x8*)(K_lds + (b) * SHM_K + KSWZ(32 + sr, kc)) = sr_[i].ks1; \
;     if constexpr (MODE == 1) *(bf16x8*)(KR_lds + (b) * SHM_KR + KRSWZ(krr, krc * 2)) = sr_[i].kr; } while (0)
; template <int MODE>
; __device__ __forceinline__ void body(const Desc& d, char* lds, int wave_id) {
;     ...
;       for (int dd = 0; dd < 2; ++dd) { bf16x8 x1 = qr[8 + dd], x2 = qr[10 + dd]; bf16x8 y1, y2;
; #pragma unroll
;         for (int e = 0; e < 8; ++e) { const f32x2 cs = rp[dd * 16 + e]; const float a = bf2f((unsigned short)x1[e]), b = bf2f((unsigned short)x2[e]);
;           const float o1 = a * cs.x - b * cs.y, o2 = b * cs.x + a * cs.y; const unsigned pk = cvt_pk_bf16(o1, o2); y1[e] = (short)(pk & 0xffff); y2[e] = (short)(pk >> 16); }
;         qr[8 + dd] = y1; qr[10 + dd] = y2; }
;     }
;   }
;   const int sr = tid >> 4, sc = (tid & 15) * 8, vst0 = v_st(sr, sc), vst1 = v_st(32 + sr, sc);
;   const int krr = tid >> 3, krc = (tid & 7) * 8;
;   const int vb0 = (int)(uintptr_t)V_lds + v_rd_base(lane);
;   struct { bf16x8 vs0, vs1, ks0, ks1, kr; } sr_[1];
;     ...
;   f32x16 pA0, pA1, pB0, pB1; float mnA, mnB, alA, alB; bf16x8 pa0, pa1, pa2, pa3; const int NT = d.NT;
;   const int tlo_ = __builtin_amdgcn_readfirstlane(wid) >> 1;
;     ...
;   constexpr int SE = 0, SO = 0;
;   SLOAD(SE, 0); asm volatile("s_waitcnt vmcnt(0)" ::: "memory"); SWRITE(0, SE); __syncthreads();
	v_pk_mul_f32 v[18:19], v[10:11], v[14:15]
	v_pk_mul_f32 v[10:11], v[10:11], v[14:15] op_sel:[0,1] op_sel_hi:[1,0]
	v_sub_f32_e32 v12, v18, v19
	v_add_f32_e32 v10, v10, v11
	v_cvt_pk_bf16_f32 v65, v12, v10
	v_mov_b32_e32 v10, v142
	v_mov_b32_e32 v11, v143
	v_and_b32_e32 v15, 0xffff0000, v17
	v_and_b32_e32 v14, 0xffff0000, v13
	v_add_u32_e32 v17, s44, v55
	v_lshl_or_b32 v56, v17, 7, v62
	v_add_u32_e32 v220, 0x4000, v56
	s_waitcnt vmcnt(0)
	v_pk_mul_f32 v[12:13], v[10:11], v[14:15]
	v_pk_mul_f32 v[10:11], v[10:11], v[14:15] op_sel:[0,1] op_sel_hi:[1,0]
	v_sub_f32_e32 v12, v12, v13
	v_add_f32_e32 v10, v10, v11
	v_cvt_pk_bf16_f32 v67, v12, v10
	v_mov_b32_e32 v10, v222
	v_mov_b32_e32 v11, v223
	v_lshlrev_b32_e32 v13, 16, v4
	v_lshlrev_b32_e32 v12, 16, v0
	s_waitcnt vmcnt(0)
	v_pk_mul_f32 v[14:15], v[10:11], v[12:13]
	v_pk_mul_f32 v[10:11], v[10:11], v[12:13] op_sel:[0,1] op_sel_hi:[1,0]
	v_sub_f32_e32 v14, v14, v15
	v_add_f32_e32 v10, v10, v11
	v_cvt_pk_bf16_f32 v64, v14, v10
	v_mov_b32_e32 v10, v224
	v_mov_b32_e32 v11, v225
	v_and_b32_e32 v13, 0xffff0000, v4
	v_and_b32_e32 v12, 0xffff0000, v0
	s_waitcnt vmcnt(0)
	v_pk_mul_f32 v[14:15], v[10:11], v[12:13]
	v_pk_mul_f32 v[10:11], v[10:11], v[12:13] op_sel:[0,1] op_sel_hi:[1,0]
	v_sub_f32_e32 v0, v14, v15
	v_add_f32_e32 v4, v10, v11
	v_cvt_pk_bf16_f32 v66, v0, v4
	v_mov_b32_e32 v10, v226
	v_mov_b32_e32 v11, v227
	v_lshlrev_b32_e32 v13, 16, v5
	v_lshlrev_b32_e32 v12, 16, v1
	v_and_b32_e32 v5, 0xffff0000, v5
	s_waitcnt vmcnt(0)
	v_pk_mul_f32 v[14:15], v[10:11], v[12:13]
	v_pk_mul_f32 v[10:11], v[10:11], v[12:13] op_sel:[0,1] op_sel_hi:[1,0]
	v_sub_f32_e32 v0, v14, v15
	v_add_f32_e32 v4, v10, v11
	v_cvt_pk_bf16_f32 v68, v0, v4
	v_mov_b32_e32 v10, v228
	v_mov_b32_e32 v11, v229
	v_and_b32_e32 v4, 0xffff0000, v1
	s_waitcnt vmcnt(0)
	v_pk_mul_f32 v[0:1], v[10:11], v[4:5]
	s_nop 0
	v_sub_f32_e32 v12, v0, v1
	v_pk_mul_f32 v[0:1], v[10:11], v[4:5] op_sel:[0,1] op_sel_hi:[1,0]
	v_lshlrev_b32_e32 v5, 16, v6
	v_add_f32_e32 v0, v0, v1
	v_cvt_pk_bf16_f32 v69, v12, v0
	v_mov_b32_e32 v0, v230
	v_mov_b32_e32 v1, v231
	v_lshlrev_b32_e32 v4, 16, v2
	s_waitcnt vmcnt(0)
	v_pk_mul_f32 v[10:11], v[0:1], v[4:5]
	v_pk_mul_f32 v[0:1], v[0:1], v[4:5] op_sel:[0,1] op_sel_hi:[1,0]
	v_sub_f32_e32 v10, v10, v11
	v_add_f32_e32 v0, v0, v1
	v_cvt_pk_bf16_f32 v70, v10, v0
	v_mov_b32_e32 v0, v232
	v_mov_b32_e32 v1, v233
	v_and_b32_e32 v5, 0xffff0000, v6
	v_and_b32_e32 v4, 0xffff0000, v2
	s_waitcnt vmcnt(0)
	v_pk_mul_f32 v[10:11], v[0:1], v[4:5]
	v_pk_mul_f32 v[0:1], v[0:1], v[4:5] op_sel:[0,1] op_sel_hi:[1,0]
	v_sub_f32_e32 v2, v10, v11
	v_add_f32_e32 v0, v0, v1
	v_cvt_pk_bf16_f32 v71, v2, v0
	v_mov_b32_e32 v0, v234
	v_mov_b32_e32 v1, v235
	v_lshlrev_b32_e32 v5, 16, v7
	v_lshlrev_b32_e32 v4, 16, v3
	s_waitcnt vmcnt(0)
	v_pk_mul_f32 v[10:11], v[0:1], v[4:5]
	v_pk_mul_f32 v[0:1], v[0:1], v[4:5] op_sel:[0,1] op_sel_hi:[1,0]
	v_sub_f32_e32 v2, v10, v11
	v_add_f32_e32 v0, v0, v1
	v_cvt_pk_bf16_f32 v72, v2, v0
	v_mov_b32_e32 v0, v236
	v_mov_b32_e32 v1, v237
	v_and_b32_e32 v5, 0xffff0000, v7
	v_and_b32_e32 v4, 0xffff0000, v3
	s_waitcnt vmcnt(0)
	v_pk_mul_f32 v[2:3], v[0:1], v[4:5]
	s_nop 0
	v_sub_f32_e32 v2, v2, v3
	v_pk_mul_f32 v[0:1], v[0:1], v[4:5] op_sel:[0,1] op_sel_hi:[1,0]
	v_and_b32_e32 v3, 3, v53
	v_add_f32_e32 v0, v0, v1
	v_cvt_pk_bf16_f32 v73, v2, v0
	v_and_b32_e32 v1, 0xfffff0, v53
	v_lshlrev_b32_e32 v2, 1, v53
	v_lshlrev_b32_e32 v0, 3, v48
	v_and_or_b32 v1, v2, 8, v1
	v_and_b32_e32 v52, 0x78, v0
	v_lshrrev_b32_e32 v2, 1, v53
	v_lshrrev_b32_e32 v1, 1, v1
	v_bfe_u32 v0, v0, 5, 2
	v_or_b32_e32 v1, v1, v0
	v_and_or_b32 v2, v2, 4, v3
	v_lshlrev_b32_e32 v20, 1, v52
	v_lshlrev_b32_e32 v1, 9, v1
	v_lshlrev_b32_e32 v2, 6, v2
	v_and_b32_e32 v3, 48, v20
	v_or3_b32 v21, v1, v2, v3
	v_and_b32_e32 v1, 0xfffff0, v54
	v_lshlrev_b32_e32 v4, 1, v54
	v_and_or_b32 v1, v4, 8, v1
	v_lshrrev_b32_e32 v1, 1, v1
	v_or_b32_e32 v0, v1, v0
	v_lshlrev_b32_e32 v0, 9, v0
	v_or3_b32 v22, v0, v2, v3
	v_lshlrev_b32_e32 v0, 3, v49
	v_and_b32_e32 v1, 0xc0, v16
	v_lshlrev_b32_e32 v2, 1, v48
	v_and_or_b32 v1, v0, 24, v1
	v_and_b32_e32 v2, 32, v2
	v_and_b32_e32 v0, 0x100, v0
	v_or3_b32 v51, v1, v2, v0
	v_mul_lo_u32 v0, v50, s97
	v_or_b32_e32 v0, v0, v52
	v_lshlrev_b32_e32 v8, 1, v0
	v_add_u32_e32 v0, s44, v54
	v_mul_lo_u32 v0, v0, s97
	v_or_b32_e32 v0, v0, v52
	v_lshlrev_b32_e32 v12, 1, v0
	global_load_dwordx4 v[0:3], v8, s[60:61] offset:256
	global_load_dwordx4 v[4:7], v12, s[60:61] offset:256
	s_nop 0
	global_load_dwordx4 v[8:11], v8, s[60:61]
	s_nop 0
	global_load_dwordx4 v[12:15], v12, s[60:61]
	v_add_u32_e32 v174, 0, v21
	global_load_dwordx4 v[16:19], v56, s[48:49]
	s_waitcnt vmcnt(0)
	v_add_u32_e32 v175, 0, v22
	v_add_u32_e32 v172, s46, v51
	s_waitcnt vmcnt(4)
	ds_write_b128 v174, v[0:3]
	v_lshlrev_b32_e32 v0, 8, v53
	v_and_b32_e32 v1, 0x70, v48
	v_bitop3_b32 v0, v20, v0, v1 bitop3:0xde
	v_add_u32_e32 v177, 0, v0
	v_lshlrev_b32_e32 v0, 8, v54
	v_bitop3_b32 v0, v20, v0, v1 bitop3:0xde
	v_xor_b32_e32 v1, v55, v48
	v_add_u32_e32 v178, 0, v0
	v_lshlrev_b32_e32 v0, 7, v55
	v_lshlrev_b32_e32 v1, 4, v1
	v_and_or_b32 v74, v1, s38, v0
	v_add_u32_e32 v0, s45, v74
	s_waitcnt vmcnt(3)
	ds_write_b128 v175, v[4:7]
	s_waitcnt vmcnt(2)
	ds_write_b128 v177, v[8:11] offset:32768
	s_waitcnt vmcnt(1)
	ds_write_b128 v178, v[12:15] offset:32768
	s_waitcnt vmcnt(0)
	ds_write_b128 v0, v[16:19]
	v_bitop3_b32 v0, v194, v75, v62 bitop3:0xde
	v_add_u32_e32 v180, 0, v0
	s_waitcnt lgkmcnt(0)
	s_barrier
; __device__ __forceinline__ unsigned cvt_pk_bf16(float lo, float hi) { unsigned r; asm volatile("v_cvt_pk_bf16_f32 %0, %1, %2" : "=v"(r) : "v"(lo), "v"(hi)); return r; }
; __device__ __forceinline__ float bf2f(unsigned short h) { return __uint_as_float(((unsigned)h) << 16); }
; template <int NQ>
; __device__ __forceinline__ void qkt(f32x16& p0, f32x16& p1, const char* Ks, const char* KRs, const bf16x8* qr, int r32, int hi) {
;   p0 = f32x16{}; p1 = f32x16{};
; #pragma unroll
;   for (int d0 = 0; d0 < 8; ++d0) { const int cb = (d0 * 16 + hi * 8) * 2;
;     bf16x8 b0 = *reinterpret_cast<const bf16x8*>(Ks + KSWZ(r32, cb));
;     bf16x8 b1 = *reinterpret_cast<const bf16x8*>(Ks + KSWZ(32 + r32, cb));
;     p0 = __builtin_amdgcn_mfma_f32_32x32x16_bf16(b0, qr[d0], p0, 0, 0, 0);
;     p1 = __builtin_amdgcn_mfma_f32_32x32x16_bf16(b1, qr[d0], p1, 0, 0, 0); }
;   if constexpr (NQ == 12) {
; #pragma unroll
;     for (int d0 = 0; d0 < 4; ++d0) { const int cb = d0 * 32 + hi * 16;
;       bf16x8 b0 = *reinterpret_cast<const bf16x8*>(KRs + KRSWZ(r32, cb));
;       bf16x8 b1 = *reinterpret_cast<const bf16x8*>(KRs + KRSWZ(32 + r32, cb));
;       p0 = __builtin_amdgcn_mfma_f32_32x32x16_bf16(b0, qr[8 + d0], p0, 0, 0, 0);
;       p1 = __builtin_amdgcn_mfma_f32_32x32x16_bf16(b1, qr[8 + d0], p1, 0, 0, 0); }
;   }
; }
; template <int MODE>
; __device__ __forceinline__ void body(const Desc& d, char* lds, int wave_id) {
;     ...
;       for (int dd = 0; dd < 2; ++dd) { bf16x8 x1 = qr[8 + dd], x2 = qr[10 + dd]; bf16x8 y1, y2;
; #pragma unroll
;         for (int e = 0; e < 8; ++e) { const f32x2 cs = rp[dd * 16 + e]; const float a = bf2f((unsigned short)x1[e]), b = bf2f((unsigned short)x2[e]);
;           const float o1 = a * cs.x - b * cs.y, o2 = b * cs.x + a * cs.y; const unsigned pk = cvt_pk_bf16(o1, o2); y1[e] = (short)(pk & 0xffff); y2[e] = (short)(pk >> 16); }
;         qr[8 + dd] = y1; qr[10 + dd] = y2; }
	ds_read_b128 v[16:19], v180 offset:32768
	ds_read_b128 v[20:23], v180 offset:40960
	s_waitcnt lgkmcnt(1)
	v_mfma_f32_32x32x16_bf16 v[32:47], v[16:19], v[124:127], 0
	ds_read_b128 v[76:79], v181 offset:32768
	ds_read_b128 v[80:83], v181 offset:40960
	s_mov_b32 s38, 0x5040100
	v_perm_b32 v128, v58, v57, s38
	v_perm_b32 v129, v60, v59, s38
	v_perm_b32 v130, v63, v61, s38
	v_perm_b32 v131, v67, v65, s38
	v_perm_b32 v132, v66, v64, s38
	s_waitcnt lgkmcnt(2)
	v_mfma_f32_32x32x16_bf16 v[16:31], v[20:23], v[124:127], 0
	v_perm_b32 v133, v69, v68, s38
	v_perm_b32 v134, v71, v70, s38
	v_perm_b32 v135, v73, v72, s38
	s_mov_b32 s38, 0x7060302
	v_perm_b32 v136, v58, v57, s38
	v_perm_b32 v137, v60, v59, s38
	v_perm_b32 v138, v63, v61, s38
	s_waitcnt lgkmcnt(1)
	v_mfma_f32_32x32x16_bf16 v[32:47], v[76:79], v[120:123], v[32:47]
	v_bitop3_b32 v76, v85, v75, v62 bitop3:0xde
	v_add_u32_e32 v182, 0, v76
	v_perm_b32 v139, v67, v65, s38
	v_perm_b32 v140, v66, v64, s38
	v_perm_b32 v141, v69, v68, s38
	v_perm_b32 v142, v71, v70, s38
	v_perm_b32 v143, v73, v72, s38
	s_waitcnt lgkmcnt(0)
	v_mfma_f32_32x32x16_bf16 v[16:31], v[80:83], v[120:123], v[16:31]
	ds_read_b128 v[76:79], v182 offset:32768
	ds_read_b128 v[80:83], v182 offset:40960
	v_mov_b64_e32 v[0:1], s[80:81]
	v_add_u32_e32 v218, 0, v74
	v_mov_b64_e32 v[14:15], s[94:95]
	v_add_u32_e32 v219, 0x12000, v218
	v_mov_b64_e32 v[2:3], s[82:83]
	v_mov_b64_e32 v[4:5], s[84:85]
	s_waitcnt lgkmcnt(1)
	v_mfma_f32_32x32x16_bf16 v[32:47], v[76:79], v[116:119], v[32:47]
	v_bitop3_b32 v76, v86, v75, v62 bitop3:0xde
	v_add_u32_e32 v183, 0, v76
	v_mov_b64_e32 v[6:7], s[86:87]
	v_mov_b64_e32 v[8:9], s[88:89]
	v_mov_b64_e32 v[10:11], s[90:91]
	v_mov_b64_e32 v[12:13], s[92:93]
	v_readlane_b32 s94, v255, 11
	s_waitcnt lgkmcnt(0)
	v_mfma_f32_32x32x16_bf16 v[16:31], v[80:83], v[116:119], v[16:31]
	ds_read_b128 v[76:79], v183 offset:32768
	ds_read_b128 v[80:83], v183 offset:40960
	s_mov_b32 s92, 0x6dc9c883
	v_readlane_b32 s95, v255, 12
	s_mov_b32 s93, 0x3fc45f30
	s_mov_b32 s91, 0x9fff
	s_mov_b32 s90, 0x8b00000
	s_waitcnt lgkmcnt(1)
	v_mfma_f32_32x32x16_bf16 v[32:47], v[76:79], v[112:115], v[32:47]
	v_or_b32_e32 v76, 0x80, v194
	v_bitop3_b32 v76, v76, v75, v62 bitop3:0xde
	v_add_u32_e32 v184, 0, v76
	s_waitcnt lgkmcnt(0)
	v_mfma_f32_32x32x16_bf16 v[16:31], v[80:83], v[112:115], v[16:31]
	ds_read_b128 v[76:79], v184 offset:32768
	ds_read_b128 v[80:83], v184 offset:40960
	s_waitcnt lgkmcnt(1)
	v_mfma_f32_32x32x16_bf16 v[32:47], v[76:79], v[108:111], v[32:47]
	v_or_b32_e32 v76, 0xa0, v194
	v_bitop3_b32 v76, v76, v75, v62 bitop3:0xde
	v_add_u32_e32 v185, 0, v76
	s_waitcnt lgkmcnt(0)
	v_mfma_f32_32x32x16_bf16 v[16:31], v[80:83], v[108:111], v[16:31]
	ds_read_b128 v[76:79], v185 offset:32768
	ds_read_b128 v[80:83], v185 offset:40960
	s_waitcnt lgkmcnt(1)
	v_mfma_f32_32x32x16_bf16 v[32:47], v[76:79], v[104:107], v[32:47]
	v_or_b32_e32 v76, 0xc0, v194
	v_bitop3_b32 v76, v76, v75, v62 bitop3:0xde
	v_add_u32_e32 v186, 0, v76
	s_waitcnt lgkmcnt(0)
	v_mfma_f32_32x32x16_bf16 v[16:31], v[80:83], v[104:107], v[16:31]
	ds_read_b128 v[76:79], v186 offset:32768
	ds_read_b128 v[80:83], v186 offset:40960
	s_waitcnt lgkmcnt(1)
	v_mfma_f32_32x32x16_bf16 v[32:47], v[76:79], v[100:103], v[32:47]
	v_or_b32_e32 v76, 0xe0, v194
	v_bitop3_b32 v75, v76, v75, v62 bitop3:0xde
	v_add_u32_e32 v187, 0, v75
	v_lshlrev_b32_e32 v75, 7, v168
	v_bitop3_b32 v188, v194, v75, v62 bitop3:0xde
	v_add_u32_e32 v189, s45, v188
	v_bitop3_b32 v190, v84, v75, v62 bitop3:0xde
	s_waitcnt lgkmcnt(0)
	v_mfma_f32_32x32x16_bf16 v[16:31], v[80:83], v[100:103], v[16:31]
	ds_read_b128 v[76:79], v187 offset:32768
	ds_read_b128 v[80:83], v187 offset:40960
	v_add_u32_e32 v191, s45, v190
	v_bitop3_b32 v192, v85, v75, v62 bitop3:0xde
	v_add_u32_e32 v193, s45, v192
	v_bitop3_b32 v214, v86, v75, v62 bitop3:0xde
	v_add_u32_e32 v215, s45, v214
	s_waitcnt lgkmcnt(1)
	v_mfma_f32_32x32x16_bf16 v[32:47], v[76:79], v[96:99], v[32:47]
	s_waitcnt lgkmcnt(0)
	v_mfma_f32_32x32x16_bf16 v[16:31], v[80:83], v[96:99], v[16:31]
	ds_read_b128 v[76:79], v189
	ds_read_b128 v[80:83], v189 offset:4096
	s_waitcnt lgkmcnt(1)
	v_mfma_f32_32x32x16_bf16 v[32:47], v[76:79], v[128:131], v[32:47]
	s_waitcnt lgkmcnt(0)
	v_mfma_f32_32x32x16_bf16 v[16:31], v[80:83], v[128:131], v[16:31]
	ds_read_b128 v[76:79], v191
	ds_read_b128 v[80:83], v191 offset:4096
	s_waitcnt lgkmcnt(1)
	v_mfma_f32_32x32x16_bf16 v[32:47], v[76:79], v[132:135], v[32:47]
	s_waitcnt lgkmcnt(0)
	v_mfma_f32_32x32x16_bf16 v[16:31], v[80:83], v[132:135], v[16:31]
	ds_read_b128 v[76:79], v193
	ds_read_b128 v[80:83], v193 offset:4096
	s_waitcnt lgkmcnt(1)
	v_mfma_f32_32x32x16_bf16 v[32:47], v[76:79], v[136:139], v[32:47]
	ds_read_b128 v[58:61], v215
	ds_read_b128 v[76:79], v215 offset:4096
	s_waitcnt lgkmcnt(1)
; #define SWRITE(b, i) do { *(bf16x8*)(V_lds + (b) * SHM_V + vst0) = sr_[i].vs0; *(bf16x8*)(V_lds + (b) * SHM_V + vst1) = sr_[i].vs1; const int kc = sc * 2; \
;     *(bf16x8*)(K_lds + (b) * SHM_K + KSWZ(sr, kc)) = sr_[i].ks0; *(bf16x8*)(K_lds + (b) * SHM_K + KSWZ(32 + sr, kc)) = sr_[i].ks1; \
;     if constexpr (MODE == 1) *(bf16x8*)(KR_lds + (b) * SHM_KR + KRSWZ(krr, krc * 2)) = sr_[i].kr; } while (0)
; #define SWAIT() asm volatile("s_waitcnt vmcnt(0)" ::: "memory")
; #define QKT(P0, P1, b, t) do { qkt<NQ>(P0, P1, K_lds + (b) * SHM_K, KR_lds + (b) * SHM_KR, qr, r32, hi); mask_tile<MODE>(P0, P1, d, t, vq, hi); } while (0)
; __device__ __forceinline__ void partialSM(f32x16& p0, f32x16& p1, float& m_reg, float& mn, float& alpha, const float C, const float THRS) {
;   float pmax = p0[0];
; #pragma unroll
;   for (int r = 1; r < 16; ++r) pmax = fmaxf(pmax, p0[r]);
; #pragma unroll
;   for (int r = 0; r < 16; ++r) pmax = fmaxf(pmax, p1[r]);
;   { auto rr = __builtin_amdgcn_permlane32_swap(__float_as_uint(pmax), __float_as_uint(pmax), false, false);
;     pmax = fmaxf(__uint_as_float(rr[0]), __uint_as_float(rr[1])); }
;   if (__builtin_expect(__all(pmax - m_reg <= THRS), 1)) { mn = m_reg; alpha = 1.f; }
;   else { mn = fmaxf(m_reg, pmax); alpha = __builtin_amdgcn_exp2f((m_reg - mn) * C); m_reg = mn; }
;   const float mnC = -mn * C;
; #pragma unroll
;   for (int r = 0; r < 16; ++r) p0[r] = fmaf(p0[r], C, mnC);
; #pragma unroll
;   for (int r = 0; r < 16; ++r) p1[r] = fmaf(p1[r], C, mnC);
; #pragma unroll
;   for (int r = 0; r < 16; ++r) p0[r] = __builtin_amdgcn_exp2f(p0[r]);
; }
; template <int MODE>
; __device__ __forceinline__ void body(const Desc& d, char* lds, int wave_id) {
;     ...
;   SLOAD(SE, 0); asm volatile("s_waitcnt vmcnt(0)" ::: "memory"); SWRITE(0, SE); __syncthreads();
;   alA = 1.f; alB = 1.f; mnA = m_reg; mnB = m_reg;
;   if (ACT(0)) { QKT(pA0, pA1, 0, 0); partialSM(pA0, pA1, m_reg, mnA, alA, d.C, d.THRS); }
;   SLOAD(SO, 1);
;   SWAIT(); SWRITE(1, SO); __syncthreads();
	v_mfma_f32_32x32x16_bf16 v[32:47], v[58:61], v[140:143], v[32:47]
	v_mfma_f32_32x32x16_bf16 v[16:31], v[80:83], v[136:139], v[16:31]
	s_nop 10
	v_max_f32_e32 v57, v33, v33
	v_max_f32_e32 v58, v32, v32
	v_max_f32_e32 v57, v58, v57
	v_max3_f32 v57, v57, v34, v35
	v_max3_f32 v57, v57, v36, v37
	v_max3_f32 v57, v57, v38, v39
	v_max3_f32 v57, v57, v40, v41
	s_waitcnt lgkmcnt(0)
	v_mfma_f32_32x32x16_bf16 v[16:31], v[76:79], v[140:143], v[16:31]
	v_max3_f32 v57, v57, v42, v43
	v_max3_f32 v57, v57, v44, v45
	v_max3_f32 v57, v57, v46, v47
	s_nop 8
	v_max3_f32 v57, v57, v16, v17
	v_max3_f32 v57, v57, v18, v19
	v_max3_f32 v57, v57, v20, v21
	v_max3_f32 v57, v57, v22, v23
	v_max3_f32 v57, v57, v24, v25
	v_max3_f32 v57, v57, v26, v27
	v_max3_f32 v57, v57, v28, v29
	v_max3_f32 v57, v57, v30, v31
	v_mov_b32_e32 v58, v57
	s_nop 1
	v_permlane32_swap_b32_e32 v57, v58
	v_max_f32_e32 v58, v58, v58
	v_max_f32_e32 v57, v57, v57
	v_max_f32_e32 v57, v57, v58
	v_add_f32_e32 v58, 0x7149f2ca, v57
	v_max_f32_e32 v57, 0xf149f2ca, v57
	v_cmp_ge_f32_e32 vcc, s13, v58
	v_sub_f32_e32 v58, 0xf149f2ca, v57
	v_mul_f32_e32 v58, 0x3dd53b94, v58
	v_exp_f32_e32 v58, v58
	s_cmp_eq_u64 vcc, exec
	s_cselect_b64 vcc, -1, 0
	v_cndmask_b32_e32 v217, v57, v209, vcc
	v_cndmask_b32_e64 v216, v58, 1.0, vcc
	v_mul_f32_e32 v58, 0xbdd53b94, v217
	s_or_b32 s38, s44, 64
	v_fma_f32 v156, v16, s16, v58
	v_fma_f32 v157, v17, s16, v58
	v_add_u32_e32 v16, s38, v53
	v_mul_lo_u32 v16, v16, s97
	v_or_b32_e32 v16, v16, v52
	v_fma_f32 v144, v24, s16, v58
	v_fma_f32 v145, v25, s16, v58
	v_lshlrev_b32_e32 v24, 1, v16
	v_add_u32_e32 v16, s38, v54
	v_mul_lo_u32 v16, v16, s97
	v_fmamk_f32 v32, v32, 0x3dd53b94, v58
	v_or_b32_e32 v16, v16, v52
	v_fma_f32 v152, v28, s16, v58
	v_fma_f32 v153, v29, s16, v58
	v_exp_f32_e32 v235, v32
	v_lshlrev_b32_e32 v28, 1, v16
	v_add_u32_e32 v32, s38, v55
	v_fmamk_f32 v33, v33, 0x3dd53b94, v58
	v_fmamk_f32 v34, v34, 0x3dd53b94, v58
	v_fmamk_f32 v35, v35, 0x3dd53b94, v58
	v_fma_f32 v150, v30, s16, v58
	v_fma_f32 v151, v31, s16, v58
	v_fma_f32 v158, v26, s16, v58
	v_fma_f32 v159, v27, s16, v58
	v_fma_f32 v146, v22, s16, v58
	v_fma_f32 v147, v23, s16, v58
	v_fma_f32 v148, v20, s16, v58
	v_fma_f32 v149, v21, s16, v58
	v_fma_f32 v154, v18, s16, v58
	v_fma_f32 v155, v19, s16, v58
	global_load_dwordx4 v[16:19], v24, s[60:61] offset:256
	global_load_dwordx4 v[20:23], v28, s[60:61] offset:256
	s_nop 0
	global_load_dwordx4 v[24:27], v24, s[60:61]
	s_nop 0
	global_load_dwordx4 v[28:31], v28, s[60:61]
	v_lshl_or_b32 v32, v32, 7, v62
	v_exp_f32_e32 v237, v33
	v_exp_f32_e32 v165, v34
	v_exp_f32_e32 v236, v35
	global_load_dwordx4 v[32:35], v32, s[48:49]
	v_mov_b32_e32 v57, v58
	v_fmamk_f32 v36, v36, 0x3dd53b94, v58
	v_fmamk_f32 v37, v37, 0x3dd53b94, v58
	v_fmamk_f32 v38, v38, 0x3dd53b94, v58
	v_fmamk_f32 v39, v39, 0x3dd53b94, v58
	v_fmamk_f32 v40, v40, 0x3dd53b94, v58
	v_fmamk_f32 v41, v41, 0x3dd53b94, v58
	v_fmamk_f32 v42, v42, 0x3dd53b94, v58
	v_fmamk_f32 v43, v43, 0x3dd53b94, v58
	v_fmamk_f32 v44, v44, 0x3dd53b94, v58
	v_fmamk_f32 v45, v45, 0x3dd53b94, v58
	v_fmamk_f32 v46, v46, 0x3dd53b94, v58
	v_fmac_f32_e32 v57, 0x3dd53b94, v47
	v_exp_f32_e32 v166, v36
	v_exp_f32_e32 v234, v37
	v_exp_f32_e32 v167, v38
	v_exp_f32_e32 v233, v39
	v_exp_f32_e32 v230, v40
	v_exp_f32_e32 v232, v41
	v_exp_f32_e32 v229, v42
	v_exp_f32_e32 v231, v43
	v_exp_f32_e32 v161, v44
	v_exp_f32_e32 v163, v45
	v_exp_f32_e32 v160, v46
	v_exp_f32_e32 v162, v57
	s_movk_i32 s38, 0xc00
	s_waitcnt vmcnt(0)
	s_waitcnt vmcnt(4)
	ds_write_b128 v174, v[16:19] offset:16384
	s_waitcnt vmcnt(3)
	ds_write_b128 v175, v[20:23] offset:16384
	s_waitcnt vmcnt(2)
	ds_write_b128 v177, v[24:27] offset:49152
	s_waitcnt vmcnt(1)
	ds_write_b128 v178, v[28:31] offset:49152
	s_addk_i32 s46, 0x4000
	v_mul_lo_u32 v16, v50, s38
	v_and_b32_e32 v17, 15, v48
	v_cmp_gt_u32_e64 s[44:45], 32, v49
	s_waitcnt vmcnt(0)
	ds_write_b128 v219, v[32:35]
	v_add_u32_e32 v176, s46, v51
	v_lshl_or_b32 v225, v17, 4, v16
	v_mov_b64_e32 v[46:47], v[14:15]
	v_mov_b64_e32 v[30:31], v[14:15]
	v_mov_b64_e32 v[62:63], v[14:15]
	v_mov_b64_e32 v[44:45], v[12:13]
	v_mov_b64_e32 v[42:43], v[10:11]
	v_mov_b64_e32 v[40:41], v[8:9]
	v_mov_b64_e32 v[38:39], v[6:7]
	v_mov_b64_e32 v[36:37], v[4:5]
	v_mov_b64_e32 v[34:35], v[2:3]
	v_mov_b64_e32 v[32:33], v[0:1]
	v_mov_b64_e32 v[28:29], v[12:13]
	v_mov_b64_e32 v[26:27], v[10:11]
	v_mov_b64_e32 v[24:25], v[8:9]
	v_mov_b64_e32 v[22:23], v[6:7]
	v_mov_b64_e32 v[20:21], v[4:5]
	v_mov_b64_e32 v[18:19], v[2:3]
	v_mov_b64_e32 v[16:17], v[0:1]
	v_mov_b64_e32 v[60:61], v[12:13]
	v_mov_b64_e32 v[58:59], v[10:11]
	v_mov_b64_e32 v[56:57], v[8:9]
	v_mov_b64_e32 v[54:55], v[6:7]
	v_mov_b64_e32 v[52:53], v[4:5]
	v_mov_b64_e32 v[50:51], v[2:3]
	v_mov_b64_e32 v[48:49], v[0:1]
	s_waitcnt lgkmcnt(0)
	s_barrier

; __device__ __forceinline__ void partialSM(f32x16& p0, f32x16& p1, float& m_reg, float& mn, float& alpha, const float C, const float THRS) {
;     ...
;   for (int r = 0; r < 16; ++r) p0[r] = fmaf(p0[r], C, mnC);
; #pragma unroll
;   for (int r = 0; r < 16; ++r) p1[r] = fmaf(p1[r], C, mnC);
; #pragma unroll
;   for (int r = 0; r < 16; ++r) p0[r] = __builtin_amdgcn_exp2f(p0[r]);
; }
; __device__ __forceinline__ void finishSM(f32x16& p0, f32x16& p1, float alpha, float& l_reg, bf16x8& pa0, bf16x8& pa1, bf16x8& pa2, bf16x8& pa3) {
; #pragma unroll
;   for (int r = 0; r < 16; ++r) p1[r] = __builtin_amdgcn_exp2f(p1[r]);
;   float ps = 0;
; #pragma unroll
;   for (int r = 0; r < 16; ++r) ps += p0[r];
; #pragma unroll
;   for (int r = 0; r < 16; ++r) ps += p1[r];
;   { auto rr = __builtin_amdgcn_permlane32_swap(__float_as_uint(ps), __float_as_uint(ps), false, false);
;     ps = __uint_as_float(rr[0]) + __uint_as_float(rr[1]); }
;   l_reg = l_reg * alpha + ps;
.LBB0_805:
	v_cndmask_b32_e64 v217, v165, v217, s[46:47]
	v_mul_f32_e32 v150, 0xbdd53b94, v217
	v_mov_b32_e32 v151, v150
	v_fmamk_f32 v80, v80, 0x3dd53b94, v150
	v_fmamk_f32 v81, v81, 0x3dd53b94, v150
	v_fmamk_f32 v82, v82, 0x3dd53b94, v150
	v_fmamk_f32 v83, v83, 0x3dd53b94, v150
	v_fmamk_f32 v84, v84, 0x3dd53b94, v150
	v_fmamk_f32 v85, v85, 0x3dd53b94, v150
	v_fmamk_f32 v86, v86, 0x3dd53b94, v150
	v_fmamk_f32 v87, v87, 0x3dd53b94, v150
	v_fmamk_f32 v88, v88, 0x3dd53b94, v150
	v_fmamk_f32 v89, v89, 0x3dd53b94, v150
	v_fmamk_f32 v90, v90, 0x3dd53b94, v150
	v_fmamk_f32 v91, v91, 0x3dd53b94, v150
	v_fmamk_f32 v92, v92, 0x3dd53b94, v150
	v_fmamk_f32 v93, v93, 0x3dd53b94, v150
	v_fmamk_f32 v94, v94, 0x3dd53b94, v150
	v_fmac_f32_e32 v151, 0x3dd53b94, v95
	v_exp_f32_e32 v235, v80
	v_exp_f32_e32 v237, v81
	v_exp_f32_e32 v165, v82
	v_exp_f32_e32 v236, v83
	v_exp_f32_e32 v166, v84
	v_exp_f32_e32 v234, v85
	v_exp_f32_e32 v167, v86
	v_exp_f32_e32 v233, v87
	v_exp_f32_e32 v230, v88
	v_exp_f32_e32 v232, v89
	v_exp_f32_e32 v229, v90
	v_exp_f32_e32 v231, v91
	v_exp_f32_e32 v161, v92
	v_exp_f32_e32 v163, v93
	v_exp_f32_e32 v160, v94
	v_exp_f32_e32 v162, v151
	v_fma_f32 v156, v64, s16, v150
	v_fma_f32 v157, v65, s16, v150
	v_add_f32_e32 v64, v226, v227
	v_fmac_f32_e32 v64, v216, v179
	v_add_f32_e32 v179, v239, v240
	s_add_i32 s71, s71, 2
	v_fma_f32 v154, v66, s16, v150
	v_fma_f32 v155, v67, s16, v150
	v_fma_f32 v148, v68, s16, v150
	v_fma_f32 v149, v69, s16, v150
	v_fma_f32 v146, v70, s16, v150
	v_fma_f32 v147, v71, s16, v150
	v_fma_f32 v144, v72, s16, v150
	v_fma_f32 v145, v73, s16, v150
	v_fma_f32 v158, v74, s16, v150
	v_fma_f32 v159, v75, s16, v150
	v_fma_f32 v152, v76, s16, v150
	v_fma_f32 v153, v77, s16, v150
	v_fma_f32 v151, v79, s16, v150
	v_fma_f32 v150, v78, s16, v150
	v_fmac_f32_e32 v179, v64, v238
	s_cmp_ge_u32 s71, s70
	v_add_u32_e32 v220, 0x4000, v220
	s_waitcnt lgkmcnt(0)
	s_barrier
	s_cbranch_scc1 .LBB0_807
	v_mov_b32_e32 v225, v228
	v_mov_b32_e32 v216, v164
	s_branch .LBB0_797

; __device__ __forceinline__ void partialSM(f32x16& p0, f32x16& p1, float& m_reg, float& mn, float& alpha, const float C, const float THRS) {
;   float pmax = p0[0];
; #pragma unroll
;   for (int r = 1; r < 16; ++r) pmax = fmaxf(pmax, p0[r]);
; #pragma unroll
;   for (int r = 0; r < 16; ++r) pmax = fmaxf(pmax, p1[r]);
;   { auto rr = __builtin_amdgcn_permlane32_swap(__float_as_uint(pmax), __float_as_uint(pmax), false, false);
;     pmax = fmaxf(__uint_as_float(rr[0]), __uint_as_float(rr[1])); }
;   if (__builtin_expect(__all(pmax - m_reg <= THRS), 1)) { mn = m_reg; alpha = 1.f; }
;   else { mn = fmaxf(m_reg, pmax); alpha = __builtin_amdgcn_exp2f((m_reg - mn) * C); m_reg = mn; }
;   const float mnC = -mn * C;
; #pragma unroll
;   for (int r = 0; r < 16; ++r) p0[r] = fmaf(p0[r], C, mnC);
; #pragma unroll
;   for (int r = 0; r < 16; ++r) p1[r] = fmaf(p1[r], C, mnC);
; #pragma unroll
;   for (int r = 0; r < 16; ++r) p0[r] = __builtin_amdgcn_exp2f(p0[r]);
; }
; template <int MODE>
; __device__ __forceinline__ void body(const Desc& d, char* lds, int wave_id) {
;     ...
;     if (ACT(j - 1)) pv_d0(o, vb0, pa0, pa1, pa2, pa3); if (ACT(j)) partialSM(pB0, pB1, m_reg, mnB, alB, d.C, d.THRS); else alB = 1.f;
.LBB0_895:
	v_cndmask_b32_e64 v144, 0, 1, s[48:49]
	v_cmp_ne_u32_e64 s[46:47], 1, v144
	s_andn2_b64 vcc, exec, s[48:49]
	v_mov_b32_e32 v144, 1.0
	s_cbranch_vccnz .LBB0_897
	v_max_f32_e32 v144, v65, v65
	v_max_f32_e32 v145, v64, v64
	v_max_f32_e32 v144, v145, v144
	v_max3_f32 v144, v144, v66, v67
	v_max3_f32 v144, v144, v68, v69
	v_max3_f32 v144, v144, v70, v71
	v_max3_f32 v144, v144, v72, v73
	v_max3_f32 v144, v144, v74, v75
	v_max3_f32 v144, v144, v76, v77
	v_max3_f32 v144, v144, v78, v79
	v_max3_f32 v144, v144, v112, v113
	v_max3_f32 v144, v144, v114, v115
	v_max3_f32 v144, v144, v116, v117
	v_max3_f32 v144, v144, v118, v119
	v_max3_f32 v144, v144, v120, v121
	v_max3_f32 v144, v144, v122, v123
	v_max3_f32 v144, v144, v124, v125
	v_max3_f32 v144, v144, v126, v127
	v_mov_b32_e32 v145, v144
	s_nop 1
	v_permlane32_swap_b32_e32 v144, v145
	v_max_f32_e32 v145, v145, v145
	v_max_f32_e32 v144, v144, v144
	v_max_f32_e32 v144, v144, v145
	v_sub_f32_e32 v145, v144, v219
	v_cmp_ge_f32_e32 vcc, s19, v145
	v_max_f32_e32 v145, v219, v219
	v_max_f32_e32 v144, v145, v144
	v_sub_f32_e32 v145, v219, v144
	v_mul_f32_e32 v145, 0x3e0293ee, v145
	v_exp_f32_e32 v145, v145
	s_cmp_eq_u64 vcc, exec
	s_cselect_b64 vcc, -1, 0
	v_cndmask_b32_e32 v219, v144, v219, vcc
	v_mul_f32_e32 v198, 0xbe0293ee, v219
	v_cndmask_b32_e64 v144, v145, 1.0, vcc
	v_mov_b32_e32 v145, v198
	v_fmamk_f32 v64, v64, 0x3e0293ee, v198
	v_fmamk_f32 v65, v65, 0x3e0293ee, v198
	v_fmamk_f32 v66, v66, 0x3e0293ee, v198
	v_fmamk_f32 v67, v67, 0x3e0293ee, v198
	v_fmamk_f32 v68, v68, 0x3e0293ee, v198
	v_fmamk_f32 v69, v69, 0x3e0293ee, v198
	v_fmamk_f32 v70, v70, 0x3e0293ee, v198
	v_fmamk_f32 v71, v71, 0x3e0293ee, v198
	v_fmamk_f32 v72, v72, 0x3e0293ee, v198
	v_fmamk_f32 v73, v73, 0x3e0293ee, v198
	v_fmamk_f32 v74, v74, 0x3e0293ee, v198
	v_fmamk_f32 v75, v75, 0x3e0293ee, v198
	v_fmamk_f32 v76, v76, 0x3e0293ee, v198
	v_fmamk_f32 v77, v77, 0x3e0293ee, v198
	v_fmamk_f32 v78, v78, 0x3e0293ee, v198
	v_fmac_f32_e32 v145, 0x3e0293ee, v79
	v_exp_f32_e32 v64, v64
	v_exp_f32_e32 v65, v65
	v_exp_f32_e32 v66, v66
	v_exp_f32_e32 v67, v67
	v_exp_f32_e32 v68, v68
	v_exp_f32_e32 v69, v69
	v_exp_f32_e32 v70, v70
	v_exp_f32_e32 v71, v71
	v_exp_f32_e32 v72, v72
	v_exp_f32_e32 v73, v73
	v_exp_f32_e32 v74, v74
	v_exp_f32_e32 v75, v75
	v_exp_f32_e32 v76, v76
	v_exp_f32_e32 v77, v77
	v_exp_f32_e32 v78, v78
	v_exp_f32_e32 v79, v145
	v_fma_f32 v126, v126, s18, v198
	v_fma_f32 v127, v127, s18, v198
	v_fma_f32 v124, v124, s18, v198
	v_fma_f32 v125, v125, s18, v198
	v_fma_f32 v122, v122, s18, v198
	v_fma_f32 v123, v123, s18, v198
	v_fma_f32 v120, v120, s18, v198
	v_fma_f32 v121, v121, s18, v198
	v_fma_f32 v118, v118, s18, v198
	v_fma_f32 v119, v119, s18, v198
	v_fma_f32 v116, v116, s18, v198
	v_fma_f32 v117, v117, s18, v198
	v_fma_f32 v114, v114, s18, v198
	v_fma_f32 v115, v115, s18, v198
	v_fma_f32 v112, v112, s18, v198
	v_fma_f32 v113, v113, s18, v198

; __device__ __forceinline__ void partialSM(f32x16& p0, f32x16& p1, float& m_reg, float& mn, float& alpha, const float C, const float THRS) {
;   float pmax = p0[0];
; #pragma unroll
;   for (int r = 1; r < 16; ++r) pmax = fmaxf(pmax, p0[r]);
; #pragma unroll
;   for (int r = 0; r < 16; ++r) pmax = fmaxf(pmax, p1[r]);
;   { auto rr = __builtin_amdgcn_permlane32_swap(__float_as_uint(pmax), __float_as_uint(pmax), false, false);
;     pmax = fmaxf(__uint_as_float(rr[0]), __uint_as_float(rr[1])); }
;   if (__builtin_expect(__all(pmax - m_reg <= THRS), 1)) { mn = m_reg; alpha = 1.f; }
;   else { mn = fmaxf(m_reg, pmax); alpha = __builtin_amdgcn_exp2f((m_reg - mn) * C); m_reg = mn; }
;   const float mnC = -mn * C;
; #pragma unroll
;   for (int r = 0; r < 16; ++r) p0[r] = fmaf(p0[r], C, mnC);
; #pragma unroll
;   for (int r = 0; r < 16; ++r) p1[r] = fmaf(p1[r], C, mnC);
; #pragma unroll
;   for (int r = 0; r < 16; ++r) p0[r] = __builtin_amdgcn_exp2f(p0[r]);
; }
; template <int MODE>
; __device__ __forceinline__ void body(const Desc& d, char* lds, int wave_id) {
;     ...
;     if (ACT(j)) pv_d0(o, vb0 + SHM_V, pa0, pa1, pa2, pa3); if (ACT(j + 1)) partialSM(pA0, pA1, m_reg, mnA, alA, d.C, d.THRS); else alA = 1.f;
.LBB0_971:
	s_and_b64 vcc, exec, s[48:49]
	v_mov_b32_e32 v244, 1.0
	s_cbranch_vccnz .LBB0_973
	v_max_f32_e32 v144, v87, v87
	v_max_f32_e32 v145, v86, v86
	v_max_f32_e32 v144, v145, v144
	v_max3_f32 v144, v144, v80, v81
	v_max3_f32 v144, v144, v82, v83
	v_max3_f32 v144, v144, v84, v85
	v_max3_f32 v144, v144, v88, v89
	v_max3_f32 v144, v144, v90, v91
	v_max3_f32 v144, v144, v92, v93
	v_max3_f32 v144, v144, v94, v95
	v_max3_f32 v144, v144, v96, v97
	v_max3_f32 v144, v144, v98, v99
	v_max3_f32 v144, v144, v100, v101
	v_max3_f32 v144, v144, v102, v103
	v_max3_f32 v144, v144, v104, v105
	v_max3_f32 v144, v144, v106, v107
	v_max3_f32 v144, v144, v108, v109
	v_max3_f32 v144, v144, v110, v111
	v_mov_b32_e32 v145, v144
	s_nop 1
	v_permlane32_swap_b32_e32 v144, v145
	v_max_f32_e32 v145, v145, v145
	v_max_f32_e32 v144, v144, v144
	v_max_f32_e32 v144, v144, v145
	v_sub_f32_e32 v145, v144, v219
	v_cmp_ge_f32_e32 vcc, s19, v145
	v_max_f32_e32 v145, v219, v219
	v_max_f32_e32 v144, v145, v144
	v_sub_f32_e32 v145, v219, v144
	v_mul_f32_e32 v145, 0x3e0293ee, v145
	s_cmp_eq_u64 vcc, exec
	v_exp_f32_e32 v145, v145
	s_cselect_b64 vcc, -1, 0
	v_cndmask_b32_e32 v219, v144, v219, vcc
	v_mul_f32_e32 v144, 0xbe0293ee, v219
	v_cndmask_b32_e64 v244, v145, 1.0, vcc
	v_mov_b32_e32 v145, v144
	v_fmamk_f32 v86, v86, 0x3e0293ee, v144
	v_fmamk_f32 v87, v87, 0x3e0293ee, v144
	v_fmamk_f32 v80, v80, 0x3e0293ee, v144
	v_fmamk_f32 v81, v81, 0x3e0293ee, v144
	v_fmamk_f32 v82, v82, 0x3e0293ee, v144
	v_fmamk_f32 v83, v83, 0x3e0293ee, v144
	v_fmamk_f32 v84, v84, 0x3e0293ee, v144
	v_fmamk_f32 v85, v85, 0x3e0293ee, v144
	v_fmamk_f32 v88, v88, 0x3e0293ee, v144
	v_fmamk_f32 v89, v89, 0x3e0293ee, v144
	v_fmamk_f32 v90, v90, 0x3e0293ee, v144
	v_fmamk_f32 v91, v91, 0x3e0293ee, v144
	v_fmamk_f32 v92, v92, 0x3e0293ee, v144
	v_fmamk_f32 v93, v93, 0x3e0293ee, v144
	v_fmamk_f32 v94, v94, 0x3e0293ee, v144
	v_fmac_f32_e32 v145, 0x3e0293ee, v95
	v_exp_f32_e32 v86, v86
	v_exp_f32_e32 v87, v87
	v_exp_f32_e32 v80, v80
	v_exp_f32_e32 v81, v81
	v_exp_f32_e32 v82, v82
	v_exp_f32_e32 v83, v83
	v_exp_f32_e32 v84, v84
	v_exp_f32_e32 v85, v85
	v_exp_f32_e32 v88, v88
	v_exp_f32_e32 v89, v89
	v_exp_f32_e32 v90, v90
	v_exp_f32_e32 v91, v91
	v_exp_f32_e32 v92, v92
	v_exp_f32_e32 v93, v93
	v_exp_f32_e32 v94, v94
	v_exp_f32_e32 v95, v145
	v_fma_f32 v110, v110, s18, v144
	v_fma_f32 v111, v111, s18, v144
	v_fma_f32 v108, v108, s18, v144
	v_fma_f32 v109, v109, s18, v144
	v_fma_f32 v106, v106, s18, v144
	v_fma_f32 v107, v107, s18, v144
	v_fma_f32 v104, v104, s18, v144
	v_fma_f32 v105, v105, s18, v144
	v_fma_f32 v102, v102, s18, v144
	v_fma_f32 v103, v103, s18, v144
	v_fma_f32 v100, v100, s18, v144
	v_fma_f32 v101, v101, s18, v144
	v_fma_f32 v98, v98, s18, v144
	v_fma_f32 v99, v99, s18, v144
	v_fma_f32 v96, v96, s18, v144
	v_fma_f32 v97, v97, s18, v144

; __device__ __forceinline__ void partialSM(f32x16& p0, f32x16& p1, float& m_reg, float& mn, float& alpha, const float C, const float THRS) {
;   float pmax = p0[0];
; #pragma unroll
;   for (int r = 1; r < 16; ++r) pmax = fmaxf(pmax, p0[r]);
; #pragma unroll
;   for (int r = 0; r < 16; ++r) pmax = fmaxf(pmax, p1[r]);
;   { auto rr = __builtin_amdgcn_permlane32_swap(__float_as_uint(pmax), __float_as_uint(pmax), false, false);
;     pmax = fmaxf(__uint_as_float(rr[0]), __uint_as_float(rr[1])); }
;   if (__builtin_expect(__all(pmax - m_reg <= THRS), 1)) { mn = m_reg; alpha = 1.f; }
;   else { mn = fmaxf(m_reg, pmax); alpha = __builtin_amdgcn_exp2f((m_reg - mn) * C); m_reg = mn; }
;   const float mnC = -mn * C;
; #pragma unroll
;   for (int r = 0; r < 16; ++r) p0[r] = fmaf(p0[r], C, mnC);
; #pragma unroll
;   for (int r = 0; r < 16; ++r) p1[r] = fmaf(p1[r], C, mnC);
; #pragma unroll
;   for (int r = 0; r < 16; ++r) p0[r] = __builtin_amdgcn_exp2f(p0[r]);
; }
; template <int MODE>
; __device__ __forceinline__ void body(const Desc& d, char* lds, int wave_id) {
;     ...
;   if (ACT(NT - 2)) pv_d0(o, vb0, pa0, pa1, pa2, pa3); if (ACT(NT - 1)) partialSM(pB0, pB1, m_reg, mnB, alB, d.C, d.THRS); else alB = 1.f;
.LBB0_985:
	v_cndmask_b32_e64 v80, 0, 1, s[50:51]
	v_cmp_ne_u32_e64 s[46:47], 1, v80
	s_andn2_b64 vcc, exec, s[50:51]
	v_mov_b32_e32 v80, 1.0
	s_cbranch_vccnz .LBB0_987
	v_max_f32_e32 v80, v65, v65
	v_max_f32_e32 v81, v64, v64
	v_max_f32_e32 v80, v81, v80
	v_max3_f32 v80, v80, v66, v67
	v_max3_f32 v80, v80, v68, v69
	v_max3_f32 v80, v80, v70, v71
	v_max3_f32 v80, v80, v72, v73
	v_max3_f32 v80, v80, v74, v75
	v_max3_f32 v80, v80, v76, v77
	v_max3_f32 v80, v80, v78, v79
	v_max3_f32 v80, v80, v112, v113
	v_max3_f32 v80, v80, v114, v115
	v_max3_f32 v80, v80, v116, v117
	v_max3_f32 v80, v80, v118, v119
	v_max3_f32 v80, v80, v120, v121
	v_max3_f32 v80, v80, v122, v123
	v_max3_f32 v80, v80, v124, v125
	v_max3_f32 v80, v80, v126, v127
	v_mov_b32_e32 v81, v80
	s_nop 1
	v_permlane32_swap_b32_e32 v80, v81
	v_max_f32_e32 v81, v81, v81
	v_max_f32_e32 v80, v80, v80
	v_max_f32_e32 v80, v80, v81
	v_sub_f32_e32 v81, v80, v219
	v_cmp_ge_f32_e32 vcc, s19, v81
	v_max_f32_e32 v81, v219, v219
	v_max_f32_e32 v80, v81, v80
	v_sub_f32_e32 v81, v219, v80
	v_mul_f32_e32 v81, 0x3e0293ee, v81
	v_exp_f32_e32 v81, v81
	s_cmp_eq_u64 vcc, exec
	s_cselect_b64 vcc, -1, 0
	v_cndmask_b32_e32 v219, v80, v219, vcc
	v_mul_f32_e32 v82, 0xbe0293ee, v219
	v_cndmask_b32_e64 v80, v81, 1.0, vcc
	v_mov_b32_e32 v81, v82
	v_fmamk_f32 v64, v64, 0x3e0293ee, v82
	v_fmamk_f32 v65, v65, 0x3e0293ee, v82
	v_fmamk_f32 v66, v66, 0x3e0293ee, v82
	v_fmamk_f32 v67, v67, 0x3e0293ee, v82
	v_fmamk_f32 v68, v68, 0x3e0293ee, v82
	v_fmamk_f32 v69, v69, 0x3e0293ee, v82
	v_fmamk_f32 v70, v70, 0x3e0293ee, v82
	v_fmamk_f32 v71, v71, 0x3e0293ee, v82
	v_fmamk_f32 v72, v72, 0x3e0293ee, v82
	v_fmamk_f32 v73, v73, 0x3e0293ee, v82
	v_fmamk_f32 v74, v74, 0x3e0293ee, v82
	v_fmamk_f32 v75, v75, 0x3e0293ee, v82
	v_fmamk_f32 v76, v76, 0x3e0293ee, v82
	v_fmamk_f32 v77, v77, 0x3e0293ee, v82
	v_fmamk_f32 v78, v78, 0x3e0293ee, v82
	v_fmac_f32_e32 v81, 0x3e0293ee, v79
	v_exp_f32_e32 v64, v64
	v_exp_f32_e32 v65, v65
	v_exp_f32_e32 v66, v66
	v_exp_f32_e32 v67, v67
	v_exp_f32_e32 v68, v68
	v_exp_f32_e32 v69, v69
	v_exp_f32_e32 v70, v70
	v_exp_f32_e32 v71, v71
	v_exp_f32_e32 v72, v72
	v_exp_f32_e32 v73, v73
	v_exp_f32_e32 v74, v74
	v_exp_f32_e32 v75, v75
	v_exp_f32_e32 v76, v76
	v_exp_f32_e32 v77, v77
	v_exp_f32_e32 v78, v78
	v_exp_f32_e32 v79, v81
	v_fma_f32 v126, v126, s18, v82
	v_fma_f32 v127, v127, s18, v82
	v_fma_f32 v124, v124, s18, v82
	v_fma_f32 v125, v125, s18, v82
	v_fma_f32 v122, v122, s18, v82
	v_fma_f32 v123, v123, s18, v82
	v_fma_f32 v120, v120, s18, v82
	v_fma_f32 v121, v121, s18, v82
	v_fma_f32 v118, v118, s18, v82
	v_fma_f32 v119, v119, s18, v82
	v_fma_f32 v116, v116, s18, v82
	v_fma_f32 v117, v117, s18, v82
	v_fma_f32 v114, v114, s18, v82
	v_fma_f32 v115, v115, s18, v82
	v_fma_f32 v112, v112, s18, v82
	v_fma_f32 v113, v113, s18, v82

; __device__ __forceinline__ void partialSM(f32x16& p0, f32x16& p1, float& m_reg, float& mn, float& alpha, const float C, const float THRS) {
;   float pmax = p0[0];
; #pragma unroll
;   for (int r = 1; r < 16; ++r) pmax = fmaxf(pmax, p0[r]);
; #pragma unroll
;   for (int r = 0; r < 16; ++r) pmax = fmaxf(pmax, p1[r]);
;   { auto rr = __builtin_amdgcn_permlane32_swap(__float_as_uint(pmax), __float_as_uint(pmax), false, false);
;     pmax = fmaxf(__uint_as_float(rr[0]), __uint_as_float(rr[1])); }
;   if (__builtin_expect(__all(pmax - m_reg <= THRS), 1)) { mn = m_reg; alpha = 1.f; }
;   else { mn = fmaxf(m_reg, pmax); alpha = __builtin_amdgcn_exp2f((m_reg - mn) * C); m_reg = mn; }
;   const float mnC = -mn * C;
; #pragma unroll
;   for (int r = 0; r < 16; ++r) p0[r] = fmaf(p0[r], C, mnC);
; #pragma unroll
;   for (int r = 0; r < 16; ++r) p1[r] = fmaf(p1[r], C, mnC);
; #pragma unroll
;   for (int r = 0; r < 16; ++r) p0[r] = __builtin_amdgcn_exp2f(p0[r]);
; }
; template <int MODE>
; __device__ __forceinline__ void body(const Desc& d, char* lds, int wave_id) {
;     ...
;     if (ACT(j - 1)) pv_d0(o, vb0, pa0, pa1, pa2, pa3); if (ACT(j)) partialSM(pB0, pB1, m_reg, mnB, alB, d.C, d.THRS); else alB = 1.f;
.LBB0_1128:
	v_cndmask_b32_e64 v144, 0, 1, s[46:47]
	v_cmp_ne_u32_e64 s[44:45], 1, v144
	s_andn2_b64 vcc, exec, s[46:47]
	v_mov_b32_e32 v243, 1.0
	s_cbranch_vccnz .LBB0_1130
	v_max_f32_e32 v144, v65, v65
	v_max_f32_e32 v145, v64, v64
	v_max_f32_e32 v144, v145, v144
	v_max3_f32 v144, v144, v66, v67
	v_max3_f32 v144, v144, v68, v69
	v_max3_f32 v144, v144, v70, v71
	v_max3_f32 v144, v144, v72, v73
	v_max3_f32 v144, v144, v74, v75
	v_max3_f32 v144, v144, v76, v77
	v_max3_f32 v144, v144, v78, v79
	v_max3_f32 v144, v144, v96, v97
	v_max3_f32 v144, v144, v98, v99
	v_max3_f32 v144, v144, v100, v101
	v_max3_f32 v144, v144, v102, v103
	v_max3_f32 v144, v144, v104, v105
	v_max3_f32 v144, v144, v106, v107
	v_max3_f32 v144, v144, v108, v109
	v_max3_f32 v144, v144, v110, v111
	v_mov_b32_e32 v145, v144
	s_nop 1
	v_permlane32_swap_b32_e32 v144, v145
	v_max_f32_e32 v145, v145, v145
	v_max_f32_e32 v144, v144, v144
	v_max_f32_e32 v144, v144, v145
	v_sub_f32_e32 v145, v144, v218
	v_cmp_ge_f32_e32 vcc, s19, v145
	v_max_f32_e32 v145, v218, v218
	v_max_f32_e32 v144, v145, v144
	v_sub_f32_e32 v145, v218, v144
	v_mul_f32_e32 v145, 0x3e0293ee, v145
	v_exp_f32_e32 v145, v145
	s_cmp_eq_u64 vcc, exec
	s_cselect_b64 vcc, -1, 0
	v_cndmask_b32_e32 v218, v144, v218, vcc
	v_mul_f32_e32 v144, 0xbe0293ee, v218
	v_cndmask_b32_e64 v243, v145, 1.0, vcc
	v_mov_b32_e32 v145, v144
	v_fmamk_f32 v64, v64, 0x3e0293ee, v144
	v_fmamk_f32 v65, v65, 0x3e0293ee, v144
	v_fmamk_f32 v66, v66, 0x3e0293ee, v144
	v_fmamk_f32 v67, v67, 0x3e0293ee, v144
	v_fmamk_f32 v68, v68, 0x3e0293ee, v144
	v_fmamk_f32 v69, v69, 0x3e0293ee, v144
	v_fmamk_f32 v70, v70, 0x3e0293ee, v144
	v_fmamk_f32 v71, v71, 0x3e0293ee, v144
	v_fmamk_f32 v72, v72, 0x3e0293ee, v144
	v_fmamk_f32 v73, v73, 0x3e0293ee, v144
	v_fmamk_f32 v74, v74, 0x3e0293ee, v144
	v_fmamk_f32 v75, v75, 0x3e0293ee, v144
	v_fmamk_f32 v76, v76, 0x3e0293ee, v144
	v_fmamk_f32 v77, v77, 0x3e0293ee, v144
	v_fmamk_f32 v78, v78, 0x3e0293ee, v144
	v_fmac_f32_e32 v145, 0x3e0293ee, v79
	v_exp_f32_e32 v64, v64
	v_exp_f32_e32 v65, v65
	v_exp_f32_e32 v66, v66
	v_exp_f32_e32 v67, v67
	v_exp_f32_e32 v68, v68
	v_exp_f32_e32 v69, v69
	v_exp_f32_e32 v70, v70
	v_exp_f32_e32 v71, v71
	v_exp_f32_e32 v72, v72
	v_exp_f32_e32 v73, v73
	v_exp_f32_e32 v74, v74
	v_exp_f32_e32 v75, v75
	v_exp_f32_e32 v76, v76
	v_exp_f32_e32 v77, v77
	v_exp_f32_e32 v78, v78
	v_exp_f32_e32 v79, v145
	v_fma_f32 v110, v110, s18, v144
	v_fma_f32 v111, v111, s18, v144
	v_fma_f32 v108, v108, s18, v144
	v_fma_f32 v109, v109, s18, v144
	v_fma_f32 v106, v106, s18, v144
	v_fma_f32 v107, v107, s18, v144
	v_fma_f32 v104, v104, s18, v144
	v_fma_f32 v105, v105, s18, v144
	v_fma_f32 v102, v102, s18, v144
	v_fma_f32 v103, v103, s18, v144
	v_fma_f32 v100, v100, s18, v144
	v_fma_f32 v101, v101, s18, v144
	v_fma_f32 v98, v98, s18, v144
	v_fma_f32 v99, v99, s18, v144
	v_fma_f32 v96, v96, s18, v144
	v_fma_f32 v97, v97, s18, v144

; __device__ __forceinline__ void partialSM(f32x16& p0, f32x16& p1, float& m_reg, float& mn, float& alpha, const float C, const float THRS) {
;   float pmax = p0[0];
; #pragma unroll
;   for (int r = 1; r < 16; ++r) pmax = fmaxf(pmax, p0[r]);
; #pragma unroll
;   for (int r = 0; r < 16; ++r) pmax = fmaxf(pmax, p1[r]);
;   { auto rr = __builtin_amdgcn_permlane32_swap(__float_as_uint(pmax), __float_as_uint(pmax), false, false);
;     pmax = fmaxf(__uint_as_float(rr[0]), __uint_as_float(rr[1])); }
;   if (__builtin_expect(__all(pmax - m_reg <= THRS), 1)) { mn = m_reg; alpha = 1.f; }
;   else { mn = fmaxf(m_reg, pmax); alpha = __builtin_amdgcn_exp2f((m_reg - mn) * C); m_reg = mn; }
;   const float mnC = -mn * C;
; #pragma unroll
;   for (int r = 0; r < 16; ++r) p0[r] = fmaf(p0[r], C, mnC);
; #pragma unroll
;   for (int r = 0; r < 16; ++r) p1[r] = fmaf(p1[r], C, mnC);
; #pragma unroll
;   for (int r = 0; r < 16; ++r) p0[r] = __builtin_amdgcn_exp2f(p0[r]);
; }
; template <int MODE>
; __device__ __forceinline__ void body(const Desc& d, char* lds, int wave_id) {
;     ...
;     if (ACT(j)) pv_d0(o, vb0 + SHM_V, pa0, pa1, pa2, pa3); if (ACT(j + 1)) partialSM(pA0, pA1, m_reg, mnA, alA, d.C, d.THRS); else alA = 1.f;
.LBB0_1204:
	s_and_b64 vcc, exec, s[46:47]
	v_mov_b32_e32 v144, 1.0
	s_cbranch_vccnz .LBB0_1206
	v_max_f32_e32 v144, v87, v87
	v_max_f32_e32 v145, v86, v86
	v_max_f32_e32 v144, v145, v144
	v_max3_f32 v144, v144, v80, v81
	v_max3_f32 v144, v144, v82, v83
	v_max3_f32 v144, v144, v84, v85
	v_max3_f32 v144, v144, v88, v89
	v_max3_f32 v144, v144, v90, v91
	v_max3_f32 v144, v144, v92, v93
	v_max3_f32 v144, v144, v94, v95
	v_max3_f32 v144, v144, v112, v113
	v_max3_f32 v144, v144, v114, v115
	v_max3_f32 v144, v144, v116, v117
	v_max3_f32 v144, v144, v118, v119
	v_max3_f32 v144, v144, v120, v121
	v_max3_f32 v144, v144, v122, v123
	v_max3_f32 v144, v144, v124, v125
	v_max3_f32 v144, v144, v126, v127
	v_mov_b32_e32 v145, v144
	s_nop 1
	v_permlane32_swap_b32_e32 v144, v145
	v_max_f32_e32 v145, v145, v145
	v_max_f32_e32 v144, v144, v144
	v_max_f32_e32 v144, v144, v145
	v_sub_f32_e32 v145, v144, v218
	v_cmp_ge_f32_e32 vcc, s19, v145
	v_max_f32_e32 v145, v218, v218
	s_cmp_eq_u64 vcc, exec
	v_max_f32_e32 v144, v145, v144
	s_cselect_b64 vcc, -1, 0
	v_sub_f32_e32 v145, v218, v144
	v_cndmask_b32_e32 v218, v144, v218, vcc
	v_mul_f32_e32 v198, 0xbe0293ee, v218
	v_mul_f32_e32 v144, 0x3e0293ee, v145
	v_mov_b32_e32 v145, v198
	v_fmamk_f32 v86, v86, 0x3e0293ee, v198
	v_fmamk_f32 v87, v87, 0x3e0293ee, v198
	v_exp_f32_e32 v144, v144
	v_fmamk_f32 v80, v80, 0x3e0293ee, v198
	v_fmamk_f32 v81, v81, 0x3e0293ee, v198
	v_fmamk_f32 v82, v82, 0x3e0293ee, v198
	v_fmamk_f32 v83, v83, 0x3e0293ee, v198
	v_fmamk_f32 v84, v84, 0x3e0293ee, v198
	v_fmamk_f32 v85, v85, 0x3e0293ee, v198
	v_fmamk_f32 v88, v88, 0x3e0293ee, v198
	v_fmamk_f32 v89, v89, 0x3e0293ee, v198
	v_fmamk_f32 v90, v90, 0x3e0293ee, v198
	v_fmamk_f32 v91, v91, 0x3e0293ee, v198
	v_fmamk_f32 v92, v92, 0x3e0293ee, v198
	v_fmamk_f32 v93, v93, 0x3e0293ee, v198
	v_fmamk_f32 v94, v94, 0x3e0293ee, v198
	v_fmac_f32_e32 v145, 0x3e0293ee, v95
	v_exp_f32_e32 v86, v86
	v_exp_f32_e32 v87, v87
	v_exp_f32_e32 v80, v80
	v_exp_f32_e32 v81, v81
	v_exp_f32_e32 v82, v82
	v_exp_f32_e32 v83, v83
	v_exp_f32_e32 v84, v84
	v_exp_f32_e32 v85, v85
	v_exp_f32_e32 v88, v88
	v_exp_f32_e32 v89, v89
	v_exp_f32_e32 v90, v90
	v_exp_f32_e32 v91, v91
	v_exp_f32_e32 v92, v92
	v_exp_f32_e32 v93, v93
	v_exp_f32_e32 v94, v94
	v_exp_f32_e32 v95, v145
	v_cndmask_b32_e64 v144, v144, 1.0, vcc
	v_fma_f32 v126, v126, s18, v198
	v_fma_f32 v127, v127, s18, v198
	v_fma_f32 v124, v124, s18, v198
	v_fma_f32 v125, v125, s18, v198
	v_fma_f32 v122, v122, s18, v198
	v_fma_f32 v123, v123, s18, v198
	v_fma_f32 v120, v120, s18, v198
	v_fma_f32 v121, v121, s18, v198
	v_fma_f32 v118, v118, s18, v198
	v_fma_f32 v119, v119, s18, v198
	v_fma_f32 v116, v116, s18, v198
	v_fma_f32 v117, v117, s18, v198
	v_fma_f32 v114, v114, s18, v198
	v_fma_f32 v115, v115, s18, v198
	v_fma_f32 v112, v112, s18, v198
	v_fma_f32 v113, v113, s18, v198

; __device__ __forceinline__ void partialSM(f32x16& p0, f32x16& p1, float& m_reg, float& mn, float& alpha, const float C, const float THRS) {
;   float pmax = p0[0];
; #pragma unroll
;   for (int r = 1; r < 16; ++r) pmax = fmaxf(pmax, p0[r]);
; #pragma unroll
;   for (int r = 0; r < 16; ++r) pmax = fmaxf(pmax, p1[r]);
;   { auto rr = __builtin_amdgcn_permlane32_swap(__float_as_uint(pmax), __float_as_uint(pmax), false, false);
;     pmax = fmaxf(__uint_as_float(rr[0]), __uint_as_float(rr[1])); }
;   if (__builtin_expect(__all(pmax - m_reg <= THRS), 1)) { mn = m_reg; alpha = 1.f; }
;   else { mn = fmaxf(m_reg, pmax); alpha = __builtin_amdgcn_exp2f((m_reg - mn) * C); m_reg = mn; }
;   const float mnC = -mn * C;
; #pragma unroll
;   for (int r = 0; r < 16; ++r) p0[r] = fmaf(p0[r], C, mnC);
; #pragma unroll
;   for (int r = 0; r < 16; ++r) p1[r] = fmaf(p1[r], C, mnC);
; #pragma unroll
;   for (int r = 0; r < 16; ++r) p0[r] = __builtin_amdgcn_exp2f(p0[r]);
; }
; template <int MODE>
; __device__ __forceinline__ void body(const Desc& d, char* lds, int wave_id) {
;     ...
;   if (ACT(NT - 2)) pv_d0(o, vb0, pa0, pa1, pa2, pa3); if (ACT(NT - 1)) partialSM(pB0, pB1, m_reg, mnB, alB, d.C, d.THRS); else alB = 1.f;
.LBB0_1282:
	v_cndmask_b32_e64 v80, 0, 1, s[46:47]
	v_cmp_ne_u32_e64 s[44:45], 1, v80
	s_andn2_b64 vcc, exec, s[46:47]
	v_mov_b32_e32 v80, 1.0
	s_cbranch_vccnz .LBB0_1284
	v_max_f32_e32 v80, v65, v65
	v_max_f32_e32 v81, v64, v64
	v_max_f32_e32 v80, v81, v80
	v_max3_f32 v80, v80, v66, v67
	v_max3_f32 v80, v80, v68, v69
	v_max3_f32 v80, v80, v70, v71
	v_max3_f32 v80, v80, v72, v73
	v_max3_f32 v80, v80, v74, v75
	v_max3_f32 v80, v80, v76, v77
	v_max3_f32 v80, v80, v78, v79
	v_max3_f32 v80, v80, v96, v97
	v_max3_f32 v80, v80, v98, v99
	v_max3_f32 v80, v80, v100, v101
	v_max3_f32 v80, v80, v102, v103
	v_max3_f32 v80, v80, v104, v105
	v_max3_f32 v80, v80, v106, v107
	v_max3_f32 v80, v80, v108, v109
	v_max3_f32 v80, v80, v110, v111
	v_mov_b32_e32 v81, v80
	s_nop 1
	v_permlane32_swap_b32_e32 v80, v81
	v_max_f32_e32 v81, v81, v81
	v_max_f32_e32 v80, v80, v80
	v_max_f32_e32 v80, v80, v81
	v_sub_f32_e32 v81, v80, v218
	v_cmp_ge_f32_e32 vcc, s19, v81
	v_max_f32_e32 v81, v218, v218
	v_max_f32_e32 v80, v81, v80
	v_sub_f32_e32 v81, v218, v80
	v_mul_f32_e32 v81, 0x3e0293ee, v81
	v_exp_f32_e32 v81, v81
	s_cmp_eq_u64 vcc, exec
	s_cselect_b64 vcc, -1, 0
	v_cndmask_b32_e32 v218, v80, v218, vcc
	v_mul_f32_e32 v82, 0xbe0293ee, v218
	v_cndmask_b32_e64 v80, v81, 1.0, vcc
	v_mov_b32_e32 v81, v82
	v_fmamk_f32 v64, v64, 0x3e0293ee, v82
	v_fmamk_f32 v65, v65, 0x3e0293ee, v82
	v_fmamk_f32 v66, v66, 0x3e0293ee, v82
	v_fmamk_f32 v67, v67, 0x3e0293ee, v82
	v_fmamk_f32 v68, v68, 0x3e0293ee, v82
	v_fmamk_f32 v69, v69, 0x3e0293ee, v82
	v_fmamk_f32 v70, v70, 0x3e0293ee, v82
	v_fmamk_f32 v71, v71, 0x3e0293ee, v82
	v_fmamk_f32 v72, v72, 0x3e0293ee, v82
	v_fmamk_f32 v73, v73, 0x3e0293ee, v82
	v_fmamk_f32 v74, v74, 0x3e0293ee, v82
	v_fmamk_f32 v75, v75, 0x3e0293ee, v82
	v_fmamk_f32 v76, v76, 0x3e0293ee, v82
	v_fmamk_f32 v77, v77, 0x3e0293ee, v82
	v_fmamk_f32 v78, v78, 0x3e0293ee, v82
	v_fmac_f32_e32 v81, 0x3e0293ee, v79
	v_exp_f32_e32 v64, v64
	v_exp_f32_e32 v65, v65
	v_exp_f32_e32 v66, v66
	v_exp_f32_e32 v67, v67
	v_exp_f32_e32 v68, v68
	v_exp_f32_e32 v69, v69
	v_exp_f32_e32 v70, v70
	v_exp_f32_e32 v71, v71
	v_exp_f32_e32 v72, v72
	v_exp_f32_e32 v73, v73
	v_exp_f32_e32 v74, v74
	v_exp_f32_e32 v75, v75
	v_exp_f32_e32 v76, v76
	v_exp_f32_e32 v77, v77
	v_exp_f32_e32 v78, v78
	v_exp_f32_e32 v79, v81
	v_fma_f32 v110, v110, s18, v82
	v_fma_f32 v111, v111, s18, v82
	v_fma_f32 v108, v108, s18, v82
	v_fma_f32 v109, v109, s18, v82
	v_fma_f32 v106, v106, s18, v82
	v_fma_f32 v107, v107, s18, v82
	v_fma_f32 v104, v104, s18, v82
	v_fma_f32 v105, v105, s18, v82
	v_fma_f32 v102, v102, s18, v82
	v_fma_f32 v103, v103, s18, v82
	v_fma_f32 v100, v100, s18, v82
	v_fma_f32 v101, v101, s18, v82
	v_fma_f32 v98, v98, s18, v82
	v_fma_f32 v99, v99, s18, v82
	v_fma_f32 v96, v96, s18, v82
	v_fma_f32 v97, v97, s18, v82

; __device__ __forceinline__ float xlane_add(float v, int lane_, int mask) { return v + __uint_as_float((unsigned)__builtin_amdgcn_ds_bpermute((lane_ ^ mask) << 2, (int)__float_as_uint(v))); }
; __device__ __forceinline__ void row_scales(const float* ssq, int mrows, int row0, int fr, int fq, float (&rsv)[2][4]) {
;     const int lane_ = fr + 16 * fq;
; #pragma unroll
;     for (int ai = 0; ai < 2; ++ai)
; #pragma unroll
;         for (int m = 0; m < 4; ++m) { const int row = row0 + ai * HALF + m * 16; float t = 0.f;
; #pragma unroll
;             for (int p = 0; p < 8; ++p) t += ((const __attribute__((address_space(1))) float*)ssq)[(size_t)(fq * 8 + p) * mrows + row];
;             t = xlane_add(t, lane_, 16); t = xlane_add(t, lane_, 32); rsv[ai][m] = rsqrtf(t * (1.f / 2048.f) + 1e-6f); }
; }
.LBB0_1478:
	v_lshl_add_u32 v142, s83, 8, v149
	v_ashrrev_i32_e32 v143, 31, v142
	v_lshl_add_u64 v[146:147], v[142:143], 2, s[54:55]
	v_lshl_add_u64 v[162:163], v[146:147], 0, v[194:195]
	s_mov_b32 s38, 0x50000
	v_add_co_u32_e32 v160, vcc, s38, v162
	s_mov_b32 s38, 0x78000
	s_nop 0
	v_addc_co_u32_e32 v161, vcc, 0, v163, vcc
	v_add_co_u32_e32 v164, vcc, s38, v162
	s_mov_b32 s38, 0xa0000
	s_nop 0
	v_addc_co_u32_e32 v165, vcc, 0, v163, vcc
	v_add_co_u32_e32 v166, vcc, s38, v162
	s_mov_b32 s38, 0xc8000
	s_nop 0
	v_addc_co_u32_e32 v167, vcc, 0, v163, vcc
	v_add_co_u32_e32 v168, vcc, s38, v162
	s_mov_b32 s38, 0xf0000
	s_nop 0
	v_addc_co_u32_e32 v169, vcc, 0, v163, vcc
	v_add_co_u32_e32 v170, vcc, s38, v162
	s_mov_b32 s38, 0x118000
	s_nop 0
	v_addc_co_u32_e32 v171, vcc, 0, v163, vcc
	v_mov_b32_e32 v141, v195
	v_add_co_u32_e32 v172, vcc, s38, v162
	v_lshl_add_u64 v[158:159], v[146:147], 0, v[140:141]
	s_nop 0
	v_addc_co_u32_e32 v173, vcc, 0, v163, vcc
	global_load_dword v151, v[162:163], off
	global_load_dword v147, v[158:159], off
	global_load_dword v155, v[164:165], off
	global_load_dword v157, v[166:167], off
	global_load_dword v175, v[168:169], off
	global_load_dword v177, v[170:171], off
	global_load_dword v153, v[160:161], off
	global_load_dword v179, v[172:173], off
	global_load_dword v150, v[162:163], off offset:64
	global_load_dword v146, v[158:159], off offset:64
	global_load_dword v152, v[160:161], off offset:64
	global_load_dword v154, v[164:165], off offset:64
	global_load_dword v156, v[166:167], off offset:64
	global_load_dword v174, v[168:169], off offset:64
	global_load_dword v176, v[170:171], off offset:64
	global_load_dword v178, v[172:173], off offset:64
	s_mov_b32 s38, 0x3a000000
	v_lshl_or_b32 v144, s89, 8, v187
	v_ashrrev_i32_e32 v145, 31, v144
	s_waitcnt vmcnt(0)
	v_pk_add_f32 v[150:151], v[150:151], 0 op_sel_hi:[1,0]
	s_nop 0
	v_pk_add_f32 v[146:147], v[150:151], v[146:147]
	s_nop 0
	v_pk_add_f32 v[146:147], v[146:147], v[152:153]
	s_nop 0
	v_pk_add_f32 v[146:147], v[146:147], v[154:155]
	s_nop 0
	v_pk_add_f32 v[146:147], v[146:147], v[156:157]
	s_nop 0
	v_pk_add_f32 v[146:147], v[146:147], v[174:175]
	s_nop 0
	v_pk_add_f32 v[146:147], v[146:147], v[176:177]
	s_nop 0
	v_pk_add_f32 v[146:147], v[146:147], v[178:179]
	ds_bpermute_b32 v151, v185, v147
	ds_bpermute_b32 v150, v185, v146
	s_waitcnt lgkmcnt(0)
	v_pk_add_f32 v[146:147], v[146:147], v[150:151]
	ds_bpermute_b32 v151, v186, v147
	ds_bpermute_b32 v150, v186, v146
	s_waitcnt lgkmcnt(0)
	v_pk_add_f32 v[146:147], v[146:147], v[150:151]
	global_load_dword v151, v[162:163], off offset:128
	global_load_dword v153, v[158:159], off offset:128
	global_load_dword v155, v[160:161], off offset:128
	global_load_dword v157, v[164:165], off offset:128
	global_load_dword v175, v[166:167], off offset:128
	global_load_dword v177, v[168:169], off offset:128
	global_load_dword v179, v[170:171], off offset:128
	global_load_dword v181, v[172:173], off offset:128
	global_load_dword v150, v[162:163], off offset:192
	global_load_dword v152, v[158:159], off offset:192
	global_load_dword v154, v[160:161], off offset:192
	global_load_dword v156, v[164:165], off offset:192
	global_load_dword v174, v[166:167], off offset:192
	global_load_dword v176, v[168:169], off offset:192
	global_load_dword v178, v[170:171], off offset:192
	global_load_dword v180, v[172:173], off offset:192
	v_fma_f32 v146, v146, s38, v196
	v_fma_f32 v147, v147, s38, v196
	s_waitcnt vmcnt(7)
	v_pk_add_f32 v[150:151], v[150:151], 0 op_sel_hi:[1,0]
	s_waitcnt vmcnt(6)
	v_pk_add_f32 v[150:151], v[150:151], v[152:153]
	v_mul_f32_e32 v141, 0x4b800000, v147
	s_waitcnt vmcnt(5)
	v_pk_add_f32 v[150:151], v[150:151], v[154:155]
	v_cmp_gt_f32_e64 s[44:45], s78, v147
	s_waitcnt vmcnt(4)
	v_pk_add_f32 v[150:151], v[150:151], v[156:157]
	v_cmp_gt_f32_e32 vcc, s78, v146
	s_waitcnt vmcnt(3)
	v_pk_add_f32 v[150:151], v[150:151], v[174:175]
	v_cndmask_b32_e64 v141, v147, v141, s[44:45]
	s_waitcnt vmcnt(2)
	v_pk_add_f32 v[150:151], v[150:151], v[176:177]
	v_rsq_f32_e32 v141, v141
	s_waitcnt vmcnt(1)
	v_pk_add_f32 v[150:151], v[150:151], v[178:179]
	v_mul_f32_e32 v143, 0x45800000, v141
	s_waitcnt vmcnt(0)
; __device__ __forceinline__ unsigned cvt_pk_bf16(float lo, float hi) { unsigned r; asm volatile("v_cvt_pk_bf16_f32 %0, %1, %2" : "=v"(r) : "v"(lo), "v"(hi)); return r; }
; __device__ __forceinline__ float xlane_add(float v, int lane_, int mask) { return v + __uint_as_float((unsigned)__builtin_amdgcn_ds_bpermute((lane_ ^ mask) << 2, (int)__float_as_uint(v))); }
; __device__ __forceinline__ void row_scales(const float* ssq, int mrows, int row0, int fr, int fq, float (&rsv)[2][4]) {
;     const int lane_ = fr + 16 * fq;
; #pragma unroll
;     for (int ai = 0; ai < 2; ++ai)
; #pragma unroll
;         for (int m = 0; m < 4; ++m) { const int row = row0 + ai * HALF + m * 16; float t = 0.f;
; #pragma unroll
;             for (int p = 0; p < 8; ++p) t += ((const __attribute__((address_space(1))) float*)ssq)[(size_t)(fq * 8 + p) * mrows + row];
;             t = xlane_add(t, lane_, 16); t = xlane_add(t, lane_, 32); rsv[ai][m] = rsqrtf(t * (1.f / 2048.f) + 1e-6f); }
; }
;     __device__ __forceinline__ void operator()(const f32x4 (&acc)[2][2][4][2], const Unit& u, int wr, int wc, int fr, int fq) const {
;     ...
;             for (int m = 0; m < 4; ++m) { bf16_t* rowp = base + (size_t)(row0 + ai * HALF + m * 16) * ld + col0;
; #pragma unroll
;                 for (int bj = 0; bj < 2; ++bj) { if (col0 + bj * HALF < nc) { const f32x4 v0 = acc[ai][bj][m][0] * rsv[ai][m], v1 = acc[ai][bj][m][1] * rsv[ai][m];
;                     u32x4 w; w.x = cvt_pk_bf16(v0[0], v0[1]); w.y = cvt_pk_bf16(v0[2], v0[3]); w.z = cvt_pk_bf16(v1[0], v1[1]); w.w = cvt_pk_bf16(v1[2], v1[3]);
;                     *(__attribute__((address_space(1))) u32x4*)(rowp + bj * HALF) = w; } } }
	v_pk_add_f32 v[150:151], v[150:151], v[180:181]
	ds_bpermute_b32 v153, v185, v151
	ds_bpermute_b32 v152, v185, v150
	v_cndmask_b32_e64 v148, v141, v143, s[44:45]
	v_cmp_gt_i32_e64 s[44:45], s61, v144
	s_waitcnt lgkmcnt(0)
	v_pk_add_f32 v[154:155], v[150:151], v[152:153]
	global_load_dword v151, v[162:163], off offset:512
	global_load_dword v153, v[158:159], off offset:512
	global_load_dword v175, v[160:161], off offset:512
	global_load_dword v177, v[164:165], off offset:512
	global_load_dword v179, v[166:167], off offset:512
	global_load_dword v181, v[168:169], off offset:512
	global_load_dword v183, v[170:171], off offset:512
	global_load_dword v191, v[172:173], off offset:512
	global_load_dword v150, v[162:163], off offset:576
	global_load_dword v152, v[158:159], off offset:576
	global_load_dword v174, v[160:161], off offset:576
	global_load_dword v176, v[164:165], off offset:576
	global_load_dword v178, v[166:167], off offset:576
	global_load_dword v180, v[168:169], off offset:576
	global_load_dword v182, v[170:171], off offset:576
	global_load_dword v190, v[172:173], off offset:576
	ds_bpermute_b32 v157, v186, v155
	ds_bpermute_b32 v156, v186, v154
	s_waitcnt vmcnt(7)
	v_pk_add_f32 v[150:151], v[150:151], 0 op_sel_hi:[1,0]
	s_waitcnt vmcnt(6)
	v_pk_add_f32 v[150:151], v[150:151], v[152:153]
	s_waitcnt vmcnt(5)
	v_pk_add_f32 v[150:151], v[150:151], v[174:175]
	s_waitcnt vmcnt(4)
	v_pk_add_f32 v[150:151], v[150:151], v[176:177]
	s_waitcnt vmcnt(3)
	v_pk_add_f32 v[150:151], v[150:151], v[178:179]
	s_waitcnt vmcnt(2)
	v_pk_add_f32 v[150:151], v[150:151], v[180:181]
	s_waitcnt vmcnt(1)
	v_pk_add_f32 v[150:151], v[150:151], v[182:183]
	s_waitcnt vmcnt(0)
	v_pk_add_f32 v[150:151], v[150:151], v[190:191]
	global_load_dword v191, v[162:163], off offset:640
	global_load_dword v193, v[158:159], off offset:640
	global_load_dword v199, v[160:161], off offset:640
	global_load_dword v183, v[164:165], off offset:640
	global_load_dword v181, v[166:167], off offset:640
	global_load_dword v179, v[168:169], off offset:640
	global_load_dword v177, v[170:171], off offset:640
	global_load_dword v175, v[172:173], off offset:640
	global_load_dword v190, v[162:163], off offset:704
	global_load_dword v192, v[158:159], off offset:704
	global_load_dword v198, v[160:161], off offset:704
	global_load_dword v182, v[164:165], off offset:704
	global_load_dword v180, v[166:167], off offset:704
	global_load_dword v178, v[168:169], off offset:704
	global_load_dword v176, v[170:171], off offset:704
	global_load_dword v174, v[172:173], off offset:704
	ds_bpermute_b32 v153, v185, v151
	ds_bpermute_b32 v152, v185, v150
	v_mad_i64_i32 v[164:165], s[38:39], s59, v142, 0
	s_waitcnt lgkmcnt(0)
	v_pk_add_f32 v[150:151], v[150:151], v[152:153]
	ds_bpermute_b32 v153, v186, v151
	ds_bpermute_b32 v152, v186, v150
	s_waitcnt vmcnt(7)
	v_pk_add_f32 v[162:163], v[190:191], 0 op_sel_hi:[1,0]
	s_waitcnt vmcnt(6)
	v_pk_add_f32 v[158:159], v[162:163], v[192:193]
	s_waitcnt vmcnt(5)
	v_pk_add_f32 v[158:159], v[158:159], v[198:199]
	s_waitcnt vmcnt(4)
	v_pk_add_f32 v[158:159], v[158:159], v[182:183]
	s_waitcnt vmcnt(3)
	v_pk_add_f32 v[158:159], v[158:159], v[180:181]
	s_waitcnt vmcnt(2)
	v_pk_add_f32 v[158:159], v[158:159], v[178:179]
	s_waitcnt vmcnt(1)
	v_pk_add_f32 v[158:159], v[158:159], v[176:177]
	s_waitcnt vmcnt(0)
	v_pk_add_f32 v[158:159], v[158:159], v[174:175]
	ds_bpermute_b32 v161, v185, v159
	ds_bpermute_b32 v160, v185, v158
	s_waitcnt lgkmcnt(0)
	v_pk_add_f32 v[160:161], v[158:159], v[160:161]
	ds_bpermute_b32 v163, v186, v161
	ds_bpermute_b32 v162, v186, v160
	v_lshl_add_u64 v[158:159], v[144:145], 1, s[46:47]
	v_lshl_add_u64 v[164:165], v[164:165], 1, v[158:159]
	s_and_saveexec_b64 s[46:47], s[44:45]
	s_mov_b32 s91, 0x9fff
	s_mov_b32 s90, 0x8b00000
	s_cbranch_execz .LBB0_1480
	v_pk_mul_f32 v[166:167], v[122:123], v[148:149] op_sel_hi:[1,0]
	v_pk_mul_f32 v[122:123], v[120:121], v[148:149] op_sel_hi:[1,0]
	v_pk_mul_f32 v[126:127], v[126:127], v[148:149] op_sel_hi:[1,0]
	v_pk_mul_f32 v[124:125], v[124:125], v[148:149] op_sel_hi:[1,0]
	s_nop 0
	v_cvt_pk_bf16_f32 v120, v124, v125
	v_cvt_pk_bf16_f32 v121, v126, v127
	v_cvt_pk_bf16_f32 v122, v122, v123
	v_cvt_pk_bf16_f32 v123, v166, v167
	global_store_dwordx4 v[164:165], v[120:123], off

; __device__ __forceinline__ unsigned cvt_pk_bf16(float lo, float hi) { unsigned r; asm volatile("v_cvt_pk_bf16_f32 %0, %1, %2" : "=v"(r) : "v"(lo), "v"(hi)); return r; }
; __device__ __forceinline__ float xlane_add(float v, int lane_, int mask) { return v + __uint_as_float((unsigned)__builtin_amdgcn_ds_bpermute((lane_ ^ mask) << 2, (int)__float_as_uint(v))); }
; __device__ __forceinline__ void row_scales(const float* ssq, int mrows, int row0, int fr, int fq, float (&rsv)[2][4]) {
;     ...
;         for (int m = 0; m < 4; ++m) { const int row = row0 + ai * HALF + m * 16; float t = 0.f;
; #pragma unroll
;             for (int p = 0; p < 8; ++p) t += ((const __attribute__((address_space(1))) float*)ssq)[(size_t)(fq * 8 + p) * mrows + row];
;             t = xlane_add(t, lane_, 16); t = xlane_add(t, lane_, 32); rsv[ai][m] = rsqrtf(t * (1.f / 2048.f) + 1e-6f); }
;     __device__ __forceinline__ void operator()(const f32x4 (&acc)[2][2][4][2], const Unit& u, int wr, int wc, int fr, int fq) const {
;     ...
;             for (int m = 0; m < 4; ++m) { bf16_t* rowp = base + (size_t)(row0 + ai * HALF + m * 16) * ld + col0;
; #pragma unroll
;                 for (int bj = 0; bj < 2; ++bj) { if (col0 + bj * HALF < nc) { const f32x4 v0 = acc[ai][bj][m][0] * rsv[ai][m], v1 = acc[ai][bj][m][1] * rsv[ai][m];
;                     u32x4 w; w.x = cvt_pk_bf16(v0[0], v0[1]); w.y = cvt_pk_bf16(v0[2], v0[3]); w.z = cvt_pk_bf16(v1[0], v1[1]); w.w = cvt_pk_bf16(v1[2], v1[3]);
;                     *(__attribute__((address_space(1))) u32x4*)(rowp + bj * HALF) = w; } } }
.LBB0_1486:
	s_or_b64 exec, exec, s[48:49]
	s_nop 0
	v_pk_add_f32 v[96:97], v[154:155], v[156:157]
	s_mov_b32 s38, 0x3a000000
	v_fma_f32 v96, v96, s38, v196
	v_fma_f32 v97, v97, s38, v196
	s_nop 0
	v_mul_f32_e32 v98, 0x4b800000, v97
	v_cmp_gt_f32_e64 s[48:49], s78, v97
	v_cmp_gt_f32_e32 vcc, s78, v96
	s_nop 0
	v_cndmask_b32_e64 v97, v97, v98, s[48:49]
	v_rsq_f32_e32 v97, v97
	v_or_b32_e32 v98, 32, v142
	v_mul_f32_e32 v99, 0x45800000, v97
	v_cndmask_b32_e64 v100, v97, v99, s[48:49]
	v_mad_i64_i32 v[98:99], s[38:39], s59, v98, 0
	v_lshl_add_u64 v[98:99], v[98:99], 1, v[158:159]
	s_and_saveexec_b64 s[48:49], s[44:45]
	s_cbranch_execz .LBB0_1488
	v_pk_mul_f32 v[102:103], v[90:91], v[100:101] op_sel_hi:[1,0]
	v_pk_mul_f32 v[90:91], v[88:89], v[100:101] op_sel_hi:[1,0]
	v_pk_mul_f32 v[94:95], v[94:95], v[100:101] op_sel_hi:[1,0]
	v_pk_mul_f32 v[92:93], v[92:93], v[100:101] op_sel_hi:[1,0]
	s_nop 0
	v_cvt_pk_bf16_f32 v88, v92, v93
	v_cvt_pk_bf16_f32 v89, v94, v95
	v_cvt_pk_bf16_f32 v90, v90, v91
	v_cvt_pk_bf16_f32 v91, v102, v103
	global_store_dwordx4 v[98:99], v[88:91], off

; __device__ __forceinline__ unsigned cvt_pk_bf16(float lo, float hi) { unsigned r; asm volatile("v_cvt_pk_bf16_f32 %0, %1, %2" : "=v"(r) : "v"(lo), "v"(hi)); return r; }
; __device__ __forceinline__ float xlane_add(float v, int lane_, int mask) { return v + __uint_as_float((unsigned)__builtin_amdgcn_ds_bpermute((lane_ ^ mask) << 2, (int)__float_as_uint(v))); }
; __device__ __forceinline__ void row_scales(const float* ssq, int mrows, int row0, int fr, int fq, float (&rsv)[2][4]) {
;     ...
;         for (int m = 0; m < 4; ++m) { const int row = row0 + ai * HALF + m * 16; float t = 0.f;
; #pragma unroll
;             for (int p = 0; p < 8; ++p) t += ((const __attribute__((address_space(1))) float*)ssq)[(size_t)(fq * 8 + p) * mrows + row];
;             t = xlane_add(t, lane_, 16); t = xlane_add(t, lane_, 32); rsv[ai][m] = rsqrtf(t * (1.f / 2048.f) + 1e-6f); }
;     __device__ __forceinline__ void operator()(const f32x4 (&acc)[2][2][4][2], const Unit& u, int wr, int wc, int fr, int fq) const {
;     ...
;             for (int m = 0; m < 4; ++m) { bf16_t* rowp = base + (size_t)(row0 + ai * HALF + m * 16) * ld + col0;
; #pragma unroll
;                 for (int bj = 0; bj < 2; ++bj) { if (col0 + bj * HALF < nc) { const f32x4 v0 = acc[ai][bj][m][0] * rsv[ai][m], v1 = acc[ai][bj][m][1] * rsv[ai][m];
;                     u32x4 w; w.x = cvt_pk_bf16(v0[0], v0[1]); w.y = cvt_pk_bf16(v0[2], v0[3]); w.z = cvt_pk_bf16(v1[0], v1[1]); w.w = cvt_pk_bf16(v1[2], v1[3]);
;                     *(__attribute__((address_space(1))) u32x4*)(rowp + bj * HALF) = w; } } }
.LBB0_1494:
	s_or_b64 exec, exec, s[48:49]
	s_nop 0
	v_pk_add_f32 v[64:65], v[150:151], v[152:153]
	s_mov_b32 s38, 0x3a000000
	v_fma_f32 v64, v64, s38, v196
	v_fma_f32 v65, v65, s38, v196
	s_nop 0
	v_mul_f32_e32 v66, 0x4b800000, v65
	v_cmp_gt_f32_e64 s[48:49], s78, v65
	v_cmp_gt_f32_e32 vcc, s78, v64
	s_nop 0
	v_cndmask_b32_e64 v65, v65, v66, s[48:49]
	v_rsq_f32_e32 v65, v65
	v_add_u32_e32 v66, 0x80, v142
	v_mul_f32_e32 v67, 0x45800000, v65
	v_cndmask_b32_e64 v68, v65, v67, s[48:49]
	v_mad_i64_i32 v[66:67], s[38:39], s59, v66, 0
	v_lshl_add_u64 v[66:67], v[66:67], 1, v[158:159]
	s_and_saveexec_b64 s[48:49], s[44:45]
	s_cbranch_execz .LBB0_1496
	v_pk_mul_f32 v[70:71], v[58:59], v[68:69] op_sel_hi:[1,0]
	v_pk_mul_f32 v[58:59], v[56:57], v[68:69] op_sel_hi:[1,0]
	v_pk_mul_f32 v[62:63], v[62:63], v[68:69] op_sel_hi:[1,0]
	v_pk_mul_f32 v[60:61], v[60:61], v[68:69] op_sel_hi:[1,0]
	s_nop 0
	v_cvt_pk_bf16_f32 v56, v60, v61
	v_cvt_pk_bf16_f32 v57, v62, v63
	v_cvt_pk_bf16_f32 v58, v58, v59
	v_cvt_pk_bf16_f32 v59, v70, v71
	global_store_dwordx4 v[66:67], v[56:59], off

; __device__ __forceinline__ unsigned cvt_pk_bf16(float lo, float hi) { unsigned r; asm volatile("v_cvt_pk_bf16_f32 %0, %1, %2" : "=v"(r) : "v"(lo), "v"(hi)); return r; }
; __device__ __forceinline__ float xlane_add(float v, int lane_, int mask) { return v + __uint_as_float((unsigned)__builtin_amdgcn_ds_bpermute((lane_ ^ mask) << 2, (int)__float_as_uint(v))); }
; __device__ __forceinline__ void row_scales(const float* ssq, int mrows, int row0, int fr, int fq, float (&rsv)[2][4]) {
;     ...
;         for (int m = 0; m < 4; ++m) { const int row = row0 + ai * HALF + m * 16; float t = 0.f;
; #pragma unroll
;             for (int p = 0; p < 8; ++p) t += ((const __attribute__((address_space(1))) float*)ssq)[(size_t)(fq * 8 + p) * mrows + row];
;             t = xlane_add(t, lane_, 16); t = xlane_add(t, lane_, 32); rsv[ai][m] = rsqrtf(t * (1.f / 2048.f) + 1e-6f); }
;     __device__ __forceinline__ void operator()(const f32x4 (&acc)[2][2][4][2], const Unit& u, int wr, int wc, int fr, int fq) const {
;     ...
;             for (int m = 0; m < 4; ++m) { bf16_t* rowp = base + (size_t)(row0 + ai * HALF + m * 16) * ld + col0;
; #pragma unroll
;                 for (int bj = 0; bj < 2; ++bj) { if (col0 + bj * HALF < nc) { const f32x4 v0 = acc[ai][bj][m][0] * rsv[ai][m], v1 = acc[ai][bj][m][1] * rsv[ai][m];
;                     u32x4 w; w.x = cvt_pk_bf16(v0[0], v0[1]); w.y = cvt_pk_bf16(v0[2], v0[3]); w.z = cvt_pk_bf16(v1[0], v1[1]); w.w = cvt_pk_bf16(v1[2], v1[3]);
;                     *(__attribute__((address_space(1))) u32x4*)(rowp + bj * HALF) = w; } } }
.LBB0_1502:
	s_or_b64 exec, exec, s[48:49]
	s_waitcnt lgkmcnt(0)
	v_pk_add_f32 v[32:33], v[160:161], v[162:163]
	s_mov_b32 s38, 0x3a000000
	v_fma_f32 v32, v32, s38, v196
	v_fma_f32 v33, v33, s38, v196
	s_nop 0
	v_mul_f32_e32 v34, 0x4b800000, v33
	v_cmp_gt_f32_e64 s[48:49], s78, v33
	v_cmp_gt_f32_e32 vcc, s78, v32
	s_nop 0
	v_cndmask_b32_e64 v33, v33, v34, s[48:49]
	v_rsq_f32_e32 v33, v33
	v_add_u32_e32 v34, 0xa0, v142
	v_mul_f32_e32 v35, 0x45800000, v33
	v_cndmask_b32_e64 v36, v33, v35, s[48:49]
	v_mad_i64_i32 v[34:35], s[38:39], s59, v34, 0
	v_lshl_add_u64 v[34:35], v[34:35], 1, v[158:159]
	s_and_saveexec_b64 s[48:49], s[44:45]
	s_cbranch_execz .LBB0_1504
	v_pk_mul_f32 v[38:39], v[26:27], v[36:37] op_sel_hi:[1,0]
	v_pk_mul_f32 v[26:27], v[24:25], v[36:37] op_sel_hi:[1,0]
	v_pk_mul_f32 v[30:31], v[30:31], v[36:37] op_sel_hi:[1,0]
	v_pk_mul_f32 v[28:29], v[28:29], v[36:37] op_sel_hi:[1,0]
	s_nop 0
	v_cvt_pk_bf16_f32 v24, v28, v29
	v_cvt_pk_bf16_f32 v25, v30, v31
	v_cvt_pk_bf16_f32 v26, v26, v27
	v_cvt_pk_bf16_f32 v27, v38, v39
	global_store_dwordx4 v[34:35], v[24:27], off
